# snake MFMA order inside each 16-MFMA block (one operand changes per step; theory: less operand toggling/power)
# speedup vs baseline: 1.0164x; 1.0164x over previous
; #define PG8_STAGE(bufoff, gbase, voff) do { _Pragma("unroll") for (int _i = 0; _i < 2; ++_i) \
;         __builtin_amdgcn_global_load_lds((const unsigned*)((const char*)(gbase) + (voff)[_i]), (PG8_LAS unsigned*)(lds + (bufoff) + ldsw + _i * 8192), 16, 0, 0); } while (0)
; #define PG8_LDA(dst, b, h) do { _Pragma("unroll") for (int m = 0; m < 4; ++m) _Pragma("unroll") for (int k = 0; k < 2; ++k) dst[m][k] = *(const PG8_LAS bf16x8*)(lds + PG8_SA(b, h) + aoff + m * 2048 + k * 1024); } while (0)
; #define PG8_LDB(dst, b, h) do { _Pragma("unroll") for (int n = 0; n < 2; ++n) _Pragma("unroll") for (int k = 0; k < 2; ++k) dst[n][k] = *(const PG8_LAS bf16x8*)(lds + PG8_SB(b, h) + boff + n * 2048 + k * 1024); } while (0)
; #define PG8_MMA(ai, bj, At, Bt) do { __builtin_amdgcn_s_setprio(1); _Pragma("unroll") for (int m = 0; m < 4; ++m) _Pragma("unroll") for (int n = 0; n < 2; ++n) _Pragma("unroll") for (int k = 0; k < 2; ++k) \
;         acc[ai][bj][m][n] = __builtin_amdgcn_mfma_f32_16x16x32_bf16(Bt[n][k], At[m][k], acc[ai][bj][m][n], 0, 0, 0); __builtin_amdgcn_s_setprio(0); } while (0)
; #define PG8_WAIT_V(n) asm volatile("s_waitcnt vmcnt(" #n ")" ::: "memory")
; #define PG8_BAR __builtin_amdgcn_s_barrier()
; template <class Epi, class Sched, bool ALIGN_EPI = false, bool SP2 = false>
; __device__ __forceinline__ void gemm_phase(PG8_LAS unsigned char* lds, const Gemm g, const Sched& S, const Epi& E) {
;     ...
;         for (int t = 0; t < nt; t += 2) {
;             const bool last = (t == nt - 2);
;             const char* a1 = cA + (size_t)(t + 1) * kstep;
;             const char* a2 = last ? nA : cA + (size_t)(t + 2) * kstep; const char* b2 = last ? nB : cB + (size_t)(t + 2) * kstep;
;             const char* a3 = a2 + kstep; const char* b3 = b2 + kstep;
;             if (last && has_next) S.a_ready(nxt);
;             if constexpr (SP2) {
;             PG8_LDB(B0, 0, 0); PG8_LDB(B1, 0, 1); PG8_SCHED; PG8_LDA(At, 0, 0); PG8_STAGE(PG8_SA(1, 1), a1 + hstep, voffA);
;             PG8_WAIT_V(8); PG8_WAIT_L(0); PG8_BAR; PG8_MMA(0, 0, At, B0); PG8_MMA(0, 1, At, B1); PG8_BAR; PG8_SCHED;
;             PG8_LDA(At, 0, 1); PG8_STAGE(PG8_SB(0, 0), b2, voffB); PG8_STAGE(PG8_SB(0, 1), b2 + hstep, voffB); PG8_STAGE(PG8_SA(0, 0), a2, voffA);
;             PG8_WAIT_V(8); PG8_WAIT_L(0); PG8_BAR; PG8_MMA(1, 0, At, B0); PG8_MMA(1, 1, At, B1); PG8_BAR; PG8_SCHED;
.LBB0_165:
	s_add_u32 s28, s26, 0xfff80080
	s_addc_u32 s29, s27, -1
	s_add_i32 s78, 0, 0x10000
	s_cmp_eq_u32 s77, 28
	s_cselect_b32 s41, s17, s29
	s_cselect_b32 s40, s25, s28
	s_cselect_b32 s29, s23, s73
	s_cselect_b32 s28, s54, s55
	s_add_i32 s80, 0, 0x14000
	v_add_u32_e32 v154, s78, v161
	v_add_u32_e32 v158, s80, v161
	ds_read_b128 v[130:133], v154
	ds_read_b128 v[146:149], v154 offset:1024
	ds_read_b128 v[150:153], v154 offset:2048
	ds_read_b128 v[154:157], v154 offset:3072
	ds_read_b128 v[180:183], v158
	ds_read_b128 v[184:187], v158 offset:1024
	ds_read_b128 v[188:191], v158 offset:2048
	ds_read_b128 v[192:195], v158 offset:3072
	v_lshl_add_u64 v[158:159], s[26:27], 0, v[142:143]
	s_add_i32 m0, s45, 0xc000
	ds_read_b128 v[196:199], v164
	ds_read_b128 v[200:203], v164 offset:1024
	ds_read_b128 v[218:221], v164 offset:2048
	ds_read_b128 v[222:225], v164 offset:3072
	ds_read_b128 v[226:229], v164 offset:4096
	ds_read_b128 v[230:233], v164 offset:5120
	ds_read_b128 v[234:237], v164 offset:6144
	ds_read_b128 v[238:241], v164 offset:7168
	global_load_lds_dwordx4 v[158:159], off
	v_lshl_add_u64 v[158:159], s[26:27], 0, v[144:145]
	s_add_i32 m0, s45, 0xe000
	s_nop 0
	global_load_lds_dwordx4 v[158:159], off
	s_waitcnt vmcnt(8)
	s_waitcnt lgkmcnt(0)
	s_barrier
	s_setprio 1
	s_waitcnt lgkmcnt(0)
	v_mfma_f32_16x16x32_bf16 v[126:129], v[130:133], v[196:199], v[126:129]
	v_mfma_f32_16x16x32_bf16 v[118:121], v[150:153], v[196:199], v[118:121]
	v_mfma_f32_16x16x32_bf16 v[102:105], v[150:153], v[218:221], v[102:105]
	v_mfma_f32_16x16x32_bf16 v[110:113], v[130:133], v[218:221], v[110:113]
	v_mfma_f32_16x16x32_bf16 v[94:97], v[130:133], v[226:229], v[94:97]
	v_mfma_f32_16x16x32_bf16 v[86:89], v[150:153], v[226:229], v[86:89]
	v_mfma_f32_16x16x32_bf16 v[70:73], v[150:153], v[234:237], v[70:73]
	v_mfma_f32_16x16x32_bf16 v[78:81], v[130:133], v[234:237], v[78:81]
	v_mfma_f32_16x16x32_bf16 v[126:129], v[146:149], v[200:203], v[126:129]
	v_mfma_f32_16x16x32_bf16 v[118:121], v[154:157], v[200:203], v[118:121]
	v_mfma_f32_16x16x32_bf16 v[102:105], v[154:157], v[222:225], v[102:105]
	v_mfma_f32_16x16x32_bf16 v[110:113], v[146:149], v[222:225], v[110:113]
	v_mfma_f32_16x16x32_bf16 v[94:97], v[146:149], v[230:233], v[94:97]
	v_mfma_f32_16x16x32_bf16 v[86:89], v[154:157], v[230:233], v[86:89]
	v_mfma_f32_16x16x32_bf16 v[70:73], v[154:157], v[238:241], v[70:73]
	v_mfma_f32_16x16x32_bf16 v[78:81], v[146:149], v[238:241], v[78:81]
	s_setprio 0
	s_setprio 1
	v_mfma_f32_16x16x32_bf16 v[122:125], v[180:183], v[196:199], v[122:125]
	v_mfma_f32_16x16x32_bf16 v[114:117], v[188:191], v[196:199], v[114:117]
	v_mfma_f32_16x16x32_bf16 v[98:101], v[188:191], v[218:221], v[98:101]
	v_mfma_f32_16x16x32_bf16 v[106:109], v[180:183], v[218:221], v[106:109]
	v_mfma_f32_16x16x32_bf16 v[90:93], v[180:183], v[226:229], v[90:93]
	v_mfma_f32_16x16x32_bf16 v[82:85], v[188:191], v[226:229], v[82:85]
	v_mfma_f32_16x16x32_bf16 v[66:69], v[188:191], v[234:237], v[66:69]
	v_mfma_f32_16x16x32_bf16 v[74:77], v[180:183], v[234:237], v[74:77]
	v_mfma_f32_16x16x32_bf16 v[122:125], v[184:187], v[200:203], v[122:125]
	v_mfma_f32_16x16x32_bf16 v[114:117], v[192:195], v[200:203], v[114:117]
	v_mfma_f32_16x16x32_bf16 v[98:101], v[192:195], v[222:225], v[98:101]
	v_mfma_f32_16x16x32_bf16 v[106:109], v[184:187], v[222:225], v[106:109]
	v_mfma_f32_16x16x32_bf16 v[90:93], v[184:187], v[230:233], v[90:93]
	v_mfma_f32_16x16x32_bf16 v[82:85], v[192:195], v[230:233], v[82:85]
	v_mfma_f32_16x16x32_bf16 v[66:69], v[192:195], v[238:241], v[66:69]
	v_mfma_f32_16x16x32_bf16 v[74:77], v[184:187], v[238:241], v[74:77]
	s_setprio 0
	s_barrier
	s_add_i32 s78, s78, s46
	v_lshl_add_u64 v[158:159], s[28:29], 0, v[0:1]
	s_mov_b32 m0, s78
	ds_read_b128 v[196:199], v164 offset:16384
	ds_read_b128 v[200:203], v164 offset:17408
	ds_read_b128 v[218:221], v164 offset:18432
	ds_read_b128 v[222:225], v164 offset:19456
	ds_read_b128 v[226:229], v164 offset:20480
	ds_read_b128 v[230:233], v164 offset:21504
	ds_read_b128 v[234:237], v164 offset:22528
	ds_read_b128 v[238:241], v164 offset:23552
	global_load_lds_dwordx4 v[158:159], off
	s_add_i32 m0, s78, 0x2000
	s_add_u32 vcc_lo, s28, 0x80000
	v_lshl_add_u64 v[166:167], s[28:29], 0, v[134:135]
	s_addc_u32 vcc_hi, s29, 0
	s_add_i32 s78, s80, s46
	global_load_lds_dwordx4 v[166:167], off
	v_lshl_add_u64 v[242:243], vcc, 0, v[0:1]
	s_mov_b32 m0, s78
	v_lshl_add_u64 v[244:245], s[40:41], 0, v[136:137]
	global_load_lds_dwordx4 v[242:243], off
	v_lshl_add_u64 v[242:243], vcc, 0, v[134:135]
	s_add_i32 m0, s78, 0x2000
	s_nop 0
	global_load_lds_dwordx4 v[242:243], off
	v_lshl_add_u64 v[242:243], s[40:41], 0, v[138:139]
	s_mov_b32 m0, s45
	s_nop 0
	global_load_lds_dwordx4 v[242:243], off
	s_mov_b32 m0, s49
	s_nop 0
	global_load_lds_dwordx4 v[244:245], off
	s_waitcnt vmcnt(8)
	s_waitcnt lgkmcnt(0)
	s_barrier
; #define PG8_STAGE(bufoff, gbase, voff) do { _Pragma("unroll") for (int _i = 0; _i < 2; ++_i) \
;         __builtin_amdgcn_global_load_lds((const unsigned*)((const char*)(gbase) + (voff)[_i]), (PG8_LAS unsigned*)(lds + (bufoff) + ldsw + _i * 8192), 16, 0, 0); } while (0)
; #define PG8_LDA(dst, b, h) do { _Pragma("unroll") for (int m = 0; m < 4; ++m) _Pragma("unroll") for (int k = 0; k < 2; ++k) dst[m][k] = *(const PG8_LAS bf16x8*)(lds + PG8_SA(b, h) + aoff + m * 2048 + k * 1024); } while (0)
; #define PG8_LDB(dst, b, h) do { _Pragma("unroll") for (int n = 0; n < 2; ++n) _Pragma("unroll") for (int k = 0; k < 2; ++k) dst[n][k] = *(const PG8_LAS bf16x8*)(lds + PG8_SB(b, h) + boff + n * 2048 + k * 1024); } while (0)
; #define PG8_MMA(ai, bj, At, Bt) do { __builtin_amdgcn_s_setprio(1); _Pragma("unroll") for (int m = 0; m < 4; ++m) _Pragma("unroll") for (int n = 0; n < 2; ++n) _Pragma("unroll") for (int k = 0; k < 2; ++k) \
;         acc[ai][bj][m][n] = __builtin_amdgcn_mfma_f32_16x16x32_bf16(Bt[n][k], At[m][k], acc[ai][bj][m][n], 0, 0, 0); __builtin_amdgcn_s_setprio(0); } while (0)
; #define PG8_WAIT_V(n) asm volatile("s_waitcnt vmcnt(" #n ")" ::: "memory")
; #define PG8_WAIT_L(n) asm volatile("s_waitcnt lgkmcnt(" #n ")" ::: "memory")
; #define PG8_BAR __builtin_amdgcn_s_barrier()
; #define PG8_SCHED __builtin_amdgcn_sched_barrier(0)
; template <class Epi, class Sched, bool ALIGN_EPI = false, bool SP2 = false>
; __device__ __forceinline__ void gemm_phase(PG8_LAS unsigned char* lds, const Gemm g, const Sched& S, const Epi& E) {
;     ...
;             PG8_WAIT_V(8); PG8_WAIT_L(0); PG8_BAR; PG8_MMA(1, 0, At, B0); PG8_MMA(1, 1, At, B1); PG8_BAR; PG8_SCHED;
;             PG8_LDB(B0, 1, 0); PG8_LDB(B1, 1, 1); PG8_SCHED; PG8_LDA(At, 1, 0); PG8_STAGE(PG8_SA(0, 1), a2 + hstep, voffA);
;             PG8_WAIT_V(8); PG8_WAIT_L(0); PG8_BAR; PG8_MMA(0, 0, At, B0); PG8_MMA(0, 1, At, B1); PG8_BAR; PG8_SCHED;
;             PG8_LDA(At, 1, 1); PG8_STAGE(PG8_SB(1, 0), b3, voffB); PG8_STAGE(PG8_SB(1, 1), b3 + hstep, voffB); PG8_STAGE(PG8_SA(1, 0), a3, voffA);
	s_setprio 1
	s_waitcnt lgkmcnt(0)
	v_mfma_f32_16x16x32_bf16 v[62:65], v[130:133], v[196:199], v[62:65]
	v_mfma_f32_16x16x32_bf16 v[54:57], v[150:153], v[196:199], v[54:57]
	v_mfma_f32_16x16x32_bf16 v[38:41], v[150:153], v[218:221], v[38:41]
	v_mfma_f32_16x16x32_bf16 v[46:49], v[130:133], v[218:221], v[46:49]
	v_mfma_f32_16x16x32_bf16 v[30:33], v[130:133], v[226:229], v[30:33]
	v_mfma_f32_16x16x32_bf16 v[22:25], v[150:153], v[226:229], v[22:25]
	v_mfma_f32_16x16x32_bf16 v[6:9], v[150:153], v[234:237], v[6:9]
	v_mfma_f32_16x16x32_bf16 v[14:17], v[130:133], v[234:237], v[14:17]
	v_mfma_f32_16x16x32_bf16 v[62:65], v[146:149], v[200:203], v[62:65]
	v_mfma_f32_16x16x32_bf16 v[54:57], v[154:157], v[200:203], v[54:57]
	v_mfma_f32_16x16x32_bf16 v[38:41], v[154:157], v[222:225], v[38:41]
	v_mfma_f32_16x16x32_bf16 v[46:49], v[146:149], v[222:225], v[46:49]
	v_mfma_f32_16x16x32_bf16 v[30:33], v[146:149], v[230:233], v[30:33]
	v_mfma_f32_16x16x32_bf16 v[22:25], v[154:157], v[230:233], v[22:25]
	v_mfma_f32_16x16x32_bf16 v[6:9], v[154:157], v[238:241], v[6:9]
	v_mfma_f32_16x16x32_bf16 v[14:17], v[146:149], v[238:241], v[14:17]
	s_setprio 0
	s_setprio 1
	v_mfma_f32_16x16x32_bf16 v[58:61], v[180:183], v[196:199], v[58:61]
	v_mfma_f32_16x16x32_bf16 v[50:53], v[188:191], v[196:199], v[50:53]
	v_mfma_f32_16x16x32_bf16 v[34:37], v[188:191], v[218:221], v[34:37]
	v_mfma_f32_16x16x32_bf16 v[42:45], v[180:183], v[218:221], v[42:45]
	v_mfma_f32_16x16x32_bf16 v[26:29], v[180:183], v[226:229], v[26:29]
	v_mfma_f32_16x16x32_bf16 v[18:21], v[188:191], v[226:229], v[18:21]
	v_mfma_f32_16x16x32_bf16 v[2:5], v[188:191], v[234:237], v[2:5]
	v_mfma_f32_16x16x32_bf16 v[10:13], v[180:183], v[234:237], v[10:13]
	v_mfma_f32_16x16x32_bf16 v[58:61], v[184:187], v[200:203], v[58:61]
	v_mfma_f32_16x16x32_bf16 v[50:53], v[192:195], v[200:203], v[50:53]
	v_mfma_f32_16x16x32_bf16 v[34:37], v[192:195], v[222:225], v[34:37]
	v_mfma_f32_16x16x32_bf16 v[42:45], v[184:187], v[222:225], v[42:45]
	v_mfma_f32_16x16x32_bf16 v[26:29], v[184:187], v[230:233], v[26:29]
	v_mfma_f32_16x16x32_bf16 v[18:21], v[192:195], v[230:233], v[18:21]
	v_mfma_f32_16x16x32_bf16 v[2:5], v[192:195], v[238:241], v[2:5]
	v_mfma_f32_16x16x32_bf16 v[10:13], v[184:187], v[238:241], v[10:13]
	s_setprio 0
	s_barrier
	s_add_i32 s78, 0, 0x18000
	s_add_i32 s80, 0, 0x1c000
	v_add_u32_e32 v154, s78, v161
	v_add_u32_e32 v165, s80, v161
	ds_read_b128 v[130:133], v154
	ds_read_b128 v[146:149], v154 offset:1024
	ds_read_b128 v[150:153], v154 offset:2048
	ds_read_b128 v[154:157], v154 offset:3072
	ds_read_b128 v[180:183], v165
	ds_read_b128 v[184:187], v165 offset:1024
	ds_read_b128 v[188:191], v165 offset:2048
	ds_read_b128 v[192:195], v165 offset:3072
	s_add_u32 s40, s40, 0x80000
	s_addc_u32 s41, s41, 0
	s_mov_b32 m0, s50
	v_lshl_add_u64 v[246:247], s[40:41], 0, v[138:139]
	ds_read_b128 v[196:199], v164 offset:32768
	ds_read_b128 v[200:203], v164 offset:33792
	ds_read_b128 v[218:221], v164 offset:34816
	ds_read_b128 v[222:225], v164 offset:35840
	ds_read_b128 v[226:229], v164 offset:36864
	ds_read_b128 v[230:233], v164 offset:37888
	ds_read_b128 v[234:237], v164 offset:38912
	ds_read_b128 v[238:241], v164 offset:39936
	global_load_lds_dwordx4 v[246:247], off
	v_lshl_add_u64 v[246:247], s[40:41], 0, v[136:137]
	s_mov_b32 m0, s51
	s_nop 0
	global_load_lds_dwordx4 v[246:247], off
	s_waitcnt vmcnt(8)
	s_waitcnt lgkmcnt(0)
	s_barrier
	s_setprio 1
	s_waitcnt lgkmcnt(0)
	v_mfma_f32_16x16x32_bf16 v[126:129], v[130:133], v[196:199], v[126:129]
	v_mfma_f32_16x16x32_bf16 v[118:121], v[150:153], v[196:199], v[118:121]
	v_mfma_f32_16x16x32_bf16 v[102:105], v[150:153], v[218:221], v[102:105]
	v_mfma_f32_16x16x32_bf16 v[110:113], v[130:133], v[218:221], v[110:113]
	v_mfma_f32_16x16x32_bf16 v[94:97], v[130:133], v[226:229], v[94:97]
	v_mfma_f32_16x16x32_bf16 v[86:89], v[150:153], v[226:229], v[86:89]
	v_mfma_f32_16x16x32_bf16 v[70:73], v[150:153], v[234:237], v[70:73]
	v_mfma_f32_16x16x32_bf16 v[78:81], v[130:133], v[234:237], v[78:81]
	v_mfma_f32_16x16x32_bf16 v[126:129], v[146:149], v[200:203], v[126:129]
	v_mfma_f32_16x16x32_bf16 v[118:121], v[154:157], v[200:203], v[118:121]
	v_mfma_f32_16x16x32_bf16 v[102:105], v[154:157], v[222:225], v[102:105]
	v_mfma_f32_16x16x32_bf16 v[110:113], v[146:149], v[222:225], v[110:113]
	v_mfma_f32_16x16x32_bf16 v[94:97], v[146:149], v[230:233], v[94:97]
	v_mfma_f32_16x16x32_bf16 v[86:89], v[154:157], v[230:233], v[86:89]
	v_mfma_f32_16x16x32_bf16 v[70:73], v[154:157], v[238:241], v[70:73]
	v_mfma_f32_16x16x32_bf16 v[78:81], v[146:149], v[238:241], v[78:81]
	s_setprio 0
	s_setprio 1
	v_mfma_f32_16x16x32_bf16 v[122:125], v[180:183], v[196:199], v[122:125]
	v_mfma_f32_16x16x32_bf16 v[114:117], v[188:191], v[196:199], v[114:117]
	v_mfma_f32_16x16x32_bf16 v[98:101], v[188:191], v[218:221], v[98:101]
	v_mfma_f32_16x16x32_bf16 v[106:109], v[180:183], v[218:221], v[106:109]
	v_mfma_f32_16x16x32_bf16 v[90:93], v[180:183], v[226:229], v[90:93]
	v_mfma_f32_16x16x32_bf16 v[82:85], v[188:191], v[226:229], v[82:85]
	v_mfma_f32_16x16x32_bf16 v[66:69], v[188:191], v[234:237], v[66:69]
	v_mfma_f32_16x16x32_bf16 v[74:77], v[180:183], v[234:237], v[74:77]
	v_mfma_f32_16x16x32_bf16 v[122:125], v[184:187], v[200:203], v[122:125]
	v_mfma_f32_16x16x32_bf16 v[114:117], v[192:195], v[200:203], v[114:117]
	v_mfma_f32_16x16x32_bf16 v[98:101], v[192:195], v[222:225], v[98:101]
	v_mfma_f32_16x16x32_bf16 v[106:109], v[184:187], v[222:225], v[106:109]
	v_mfma_f32_16x16x32_bf16 v[90:93], v[184:187], v[230:233], v[90:93]
	v_mfma_f32_16x16x32_bf16 v[82:85], v[192:195], v[230:233], v[82:85]
	v_mfma_f32_16x16x32_bf16 v[66:69], v[192:195], v[238:241], v[66:69]
	v_mfma_f32_16x16x32_bf16 v[74:77], v[184:187], v[238:241], v[74:77]
	s_setprio 0
	s_barrier
; #define PG8_STAGE(bufoff, gbase, voff) do { _Pragma("unroll") for (int _i = 0; _i < 2; ++_i) \
;         __builtin_amdgcn_global_load_lds((const unsigned*)((const char*)(gbase) + (voff)[_i]), (PG8_LAS unsigned*)(lds + (bufoff) + ldsw + _i * 8192), 16, 0, 0); } while (0)
; #define PG8_LDA(dst, b, h) do { _Pragma("unroll") for (int m = 0; m < 4; ++m) _Pragma("unroll") for (int k = 0; k < 2; ++k) dst[m][k] = *(const PG8_LAS bf16x8*)(lds + PG8_SA(b, h) + aoff + m * 2048 + k * 1024); } while (0)
; #define PG8_MMA(ai, bj, At, Bt) do { __builtin_amdgcn_s_setprio(1); _Pragma("unroll") for (int m = 0; m < 4; ++m) _Pragma("unroll") for (int n = 0; n < 2; ++n) _Pragma("unroll") for (int k = 0; k < 2; ++k) \
;         acc[ai][bj][m][n] = __builtin_amdgcn_mfma_f32_16x16x32_bf16(Bt[n][k], At[m][k], acc[ai][bj][m][n], 0, 0, 0); __builtin_amdgcn_s_setprio(0); } while (0)
; #define PG8_WAIT_V(n) asm volatile("s_waitcnt vmcnt(" #n ")" ::: "memory")
; #define PG8_WAIT_L(n) asm volatile("s_waitcnt lgkmcnt(" #n ")" ::: "memory")
; #define PG8_BAR __builtin_amdgcn_s_barrier()
; #define PG8_SCHED __builtin_amdgcn_sched_barrier(0)
; template <class Epi, class Sched, bool ALIGN_EPI = false, bool SP2 = false>
; __device__ __forceinline__ void gemm_phase(PG8_LAS unsigned char* lds, const Gemm g, const Sched& S, const Epi& E) {
;     ...
;             PG8_LDA(At, 1, 1); PG8_STAGE(PG8_SB(1, 0), b3, voffB); PG8_STAGE(PG8_SB(1, 1), b3 + hstep, voffB); PG8_STAGE(PG8_SA(1, 0), a3, voffA);
;             PG8_WAIT_V(8); PG8_WAIT_L(0); PG8_BAR; PG8_MMA(1, 0, At, B0); PG8_MMA(1, 1, At, B1); PG8_BAR; PG8_SCHED;
	s_add_i32 s40, s78, s46
	v_lshl_add_u64 v[158:159], v[158:159], 0, s[34:35]
	s_mov_b32 m0, s40
	ds_read_b128 v[196:199], v164 offset:49152
	ds_read_b128 v[200:203], v164 offset:50176
	ds_read_b128 v[218:221], v164 offset:51200
	ds_read_b128 v[222:225], v164 offset:52224
	ds_read_b128 v[226:229], v164 offset:53248
	ds_read_b128 v[230:233], v164 offset:54272
	ds_read_b128 v[234:237], v164 offset:55296
	ds_read_b128 v[238:241], v164 offset:56320
	global_load_lds_dwordx4 v[158:159], off
	s_add_i32 m0, s40, 0x2000
	s_add_u32 s28, s28, 0x80080
	v_lshl_add_u64 v[158:159], v[166:167], 0, s[34:35]
	s_addc_u32 s29, s29, 0
	s_add_i32 s40, s80, s46
	global_load_lds_dwordx4 v[158:159], off
	v_lshl_add_u64 v[158:159], s[28:29], 0, v[0:1]
	s_mov_b32 m0, s40
	s_nop 0
	global_load_lds_dwordx4 v[158:159], off
	v_lshl_add_u64 v[158:159], s[28:29], 0, v[134:135]
	s_add_i32 m0, s40, 0x2000
	s_nop 0
	global_load_lds_dwordx4 v[158:159], off
	v_lshl_add_u64 v[158:159], v[242:243], 0, s[34:35]
	s_mov_b32 m0, s4
	s_nop 0
	global_load_lds_dwordx4 v[158:159], off
	v_lshl_add_u64 v[158:159], v[244:245], 0, s[34:35]
	s_mov_b32 m0, s52
	s_nop 0
	global_load_lds_dwordx4 v[158:159], off
	s_waitcnt vmcnt(8)
	s_waitcnt lgkmcnt(0)
	s_barrier
	s_setprio 1
	s_waitcnt lgkmcnt(0)
	v_mfma_f32_16x16x32_bf16 v[62:65], v[130:133], v[196:199], v[62:65]
	v_mfma_f32_16x16x32_bf16 v[54:57], v[150:153], v[196:199], v[54:57]
	v_mfma_f32_16x16x32_bf16 v[38:41], v[150:153], v[218:221], v[38:41]
	v_mfma_f32_16x16x32_bf16 v[46:49], v[130:133], v[218:221], v[46:49]
	v_mfma_f32_16x16x32_bf16 v[30:33], v[130:133], v[226:229], v[30:33]
	v_mfma_f32_16x16x32_bf16 v[22:25], v[150:153], v[226:229], v[22:25]
	v_mfma_f32_16x16x32_bf16 v[6:9], v[150:153], v[234:237], v[6:9]
	v_mfma_f32_16x16x32_bf16 v[14:17], v[130:133], v[234:237], v[14:17]
	v_mfma_f32_16x16x32_bf16 v[62:65], v[146:149], v[200:203], v[62:65]
	v_mfma_f32_16x16x32_bf16 v[54:57], v[154:157], v[200:203], v[54:57]
	v_mfma_f32_16x16x32_bf16 v[38:41], v[154:157], v[222:225], v[38:41]
	v_mfma_f32_16x16x32_bf16 v[46:49], v[146:149], v[222:225], v[46:49]
	v_mfma_f32_16x16x32_bf16 v[30:33], v[146:149], v[230:233], v[30:33]
	v_mfma_f32_16x16x32_bf16 v[22:25], v[154:157], v[230:233], v[22:25]
	v_mfma_f32_16x16x32_bf16 v[6:9], v[154:157], v[238:241], v[6:9]
	v_mfma_f32_16x16x32_bf16 v[14:17], v[146:149], v[238:241], v[14:17]
	s_setprio 0
	s_setprio 1
	v_mfma_f32_16x16x32_bf16 v[58:61], v[180:183], v[196:199], v[58:61]
	v_mfma_f32_16x16x32_bf16 v[50:53], v[188:191], v[196:199], v[50:53]
	v_mfma_f32_16x16x32_bf16 v[34:37], v[188:191], v[218:221], v[34:37]
	v_mfma_f32_16x16x32_bf16 v[42:45], v[180:183], v[218:221], v[42:45]
	v_mfma_f32_16x16x32_bf16 v[26:29], v[180:183], v[226:229], v[26:29]
	v_mfma_f32_16x16x32_bf16 v[18:21], v[188:191], v[226:229], v[18:21]
	v_mfma_f32_16x16x32_bf16 v[2:5], v[188:191], v[234:237], v[2:5]
	v_mfma_f32_16x16x32_bf16 v[10:13], v[180:183], v[234:237], v[10:13]
	v_mfma_f32_16x16x32_bf16 v[58:61], v[184:187], v[200:203], v[58:61]
	v_mfma_f32_16x16x32_bf16 v[50:53], v[192:195], v[200:203], v[50:53]
	v_mfma_f32_16x16x32_bf16 v[34:37], v[192:195], v[222:225], v[34:37]
	v_mfma_f32_16x16x32_bf16 v[42:45], v[184:187], v[222:225], v[42:45]
	v_mfma_f32_16x16x32_bf16 v[26:29], v[184:187], v[230:233], v[26:29]
	v_mfma_f32_16x16x32_bf16 v[18:21], v[192:195], v[230:233], v[18:21]
	v_mfma_f32_16x16x32_bf16 v[2:5], v[192:195], v[238:241], v[2:5]
	v_mfma_f32_16x16x32_bf16 v[10:13], v[184:187], v[238:241], v[10:13]
	s_setprio 0
	s_barrier
	s_add_i32 s77, s77, 2
	s_add_u32 s26, s26, 0x100
	s_addc_u32 s27, s27, 0
	s_add_u32 s55, s55, 0x100
	s_addc_u32 s73, s73, 0
	s_cmp_gt_u32 s77, 29
	s_cbranch_scc0 .LBB0_165
	s_and_b64 vcc, exec, s[20:21]
	s_cbranch_vccz .LBB0_168
	s_barrier

; #define PG8_STAGE(bufoff, gbase, voff) do { _Pragma("unroll") for (int _i = 0; _i < 2; ++_i) \
;         __builtin_amdgcn_global_load_lds((const unsigned*)((const char*)(gbase) + (voff)[_i]), (PG8_LAS unsigned*)(lds + (bufoff) + ldsw + _i * 8192), 16, 0, 0); } while (0)
; #define PG8_LDA(dst, b, h) do { _Pragma("unroll") for (int m = 0; m < 4; ++m) _Pragma("unroll") for (int k = 0; k < 2; ++k) dst[m][k] = *(const PG8_LAS bf16x8*)(lds + PG8_SA(b, h) + aoff + m * 2048 + k * 1024); } while (0)
; #define PG8_LDB(dst, b, h) do { _Pragma("unroll") for (int n = 0; n < 2; ++n) _Pragma("unroll") for (int k = 0; k < 2; ++k) dst[n][k] = *(const PG8_LAS bf16x8*)(lds + PG8_SB(b, h) + boff + n * 2048 + k * 1024); } while (0)
; #define PG8_MMA(ai, bj, At, Bt) do { __builtin_amdgcn_s_setprio(1); _Pragma("unroll") for (int m = 0; m < 4; ++m) _Pragma("unroll") for (int n = 0; n < 2; ++n) _Pragma("unroll") for (int k = 0; k < 2; ++k) \
;         acc[ai][bj][m][n] = __builtin_amdgcn_mfma_f32_16x16x32_bf16(Bt[n][k], At[m][k], acc[ai][bj][m][n], 0, 0, 0); __builtin_amdgcn_s_setprio(0); } while (0)
; #define PG8_WAIT_V(n) asm volatile("s_waitcnt vmcnt(" #n ")" ::: "memory")
; #define PG8_BAR __builtin_amdgcn_s_barrier()
; template <class Epi, class Sched, bool ALIGN_EPI = false, bool SP2 = false>
; __device__ __forceinline__ void gemm_phase(PG8_LAS unsigned char* lds, const Gemm g, const Sched& S, const Epi& E) {
;     ...
;         for (int t = 0; t < nt; t += 2) {
;             const bool last = (t == nt - 2);
;             const char* a1 = cA + (size_t)(t + 1) * kstep;
;             const char* a2 = last ? nA : cA + (size_t)(t + 2) * kstep; const char* b2 = last ? nB : cB + (size_t)(t + 2) * kstep;
;             const char* a3 = a2 + kstep; const char* b3 = b2 + kstep;
;             if (last && has_next) S.a_ready(nxt);
;             if constexpr (SP2) {
;             PG8_LDB(B0, 0, 0); PG8_LDB(B1, 0, 1); PG8_SCHED; PG8_LDA(At, 0, 0); PG8_STAGE(PG8_SA(1, 1), a1 + hstep, voffA);
;             PG8_WAIT_V(8); PG8_WAIT_L(0); PG8_BAR; PG8_MMA(0, 0, At, B0); PG8_MMA(0, 1, At, B1); PG8_BAR; PG8_SCHED;
;             PG8_LDA(At, 0, 1); PG8_STAGE(PG8_SB(0, 0), b2, voffB); PG8_STAGE(PG8_SB(0, 1), b2 + hstep, voffB); PG8_STAGE(PG8_SA(0, 0), a2, voffA);
;             PG8_WAIT_V(8); PG8_WAIT_L(0); PG8_BAR; PG8_MMA(1, 0, At, B0); PG8_MMA(1, 1, At, B1); PG8_BAR; PG8_SCHED;
.LBB0_429:
	s_add_u32 s26, s16, 0xfffc0080
	s_addc_u32 s27, s17, -1
	s_add_i32 s54, 0, 0x10000
	s_cmp_eq_u32 s78, 12
	s_cselect_b32 s29, s21, s27
	s_cselect_b32 s28, s52, s26
	v_add_u32_e32 v0, s54, v218
	s_cselect_b32 s27, s19, s77
	s_cselect_b32 s26, s53, s73
	s_add_i32 s55, 0, 0x14000
	ds_read_b128 v[52:55], v0
	ds_read_b128 v[56:59], v0 offset:1024
	ds_read_b128 v[92:95], v0 offset:2048
	ds_read_b128 v[96:99], v0 offset:3072
	v_add_u32_e32 v0, s55, v218
	ds_read_b128 v[124:127], v0
	ds_read_b128 v[128:131], v0 offset:1024
	ds_read_b128 v[148:151], v0 offset:2048
	ds_read_b128 v[152:155], v0 offset:3072
	v_lshl_add_u64 v[2:3], s[16:17], 0, v[188:189]
	s_add_i32 m0, s37, 0xc000
	ds_read_b128 v[164:167], v220
	ds_read_b128 v[192:195], v220 offset:1024
	ds_read_b128 v[196:199], v220 offset:2048
	ds_read_b128 v[200:203], v220 offset:3072
	ds_read_b128 v[222:225], v220 offset:4096
	ds_read_b128 v[226:229], v220 offset:5120
	ds_read_b128 v[230:233], v220 offset:6144
	ds_read_b128 v[234:237], v220 offset:7168
	global_load_lds_dwordx4 v[2:3], off
	v_lshl_add_u64 v[2:3], s[16:17], 0, v[190:191]
	s_add_i32 m0, s37, 0xe000
	s_nop 0
	global_load_lds_dwordx4 v[2:3], off
	s_waitcnt vmcnt(8)
	s_waitcnt lgkmcnt(0)
	s_barrier
	s_setprio 1
	s_waitcnt lgkmcnt(0)
	v_mfma_f32_16x16x32_bf16 v[88:91], v[52:55], v[164:167], v[88:91]
	v_mfma_f32_16x16x32_bf16 v[84:87], v[92:95], v[164:167], v[84:87]
	v_mfma_f32_16x16x32_bf16 v[108:111], v[92:95], v[196:199], v[108:111]
	v_mfma_f32_16x16x32_bf16 v[120:123], v[52:55], v[196:199], v[120:123]
	v_mfma_f32_16x16x32_bf16 v[136:139], v[52:55], v[222:225], v[136:139]
	v_mfma_f32_16x16x32_bf16 v[132:135], v[92:95], v[222:225], v[132:135]
	v_mfma_f32_16x16x32_bf16 v[100:103], v[92:95], v[230:233], v[100:103]
	v_mfma_f32_16x16x32_bf16 v[104:107], v[52:55], v[230:233], v[104:107]
	v_mfma_f32_16x16x32_bf16 v[88:91], v[56:59], v[192:195], v[88:91]
	v_mfma_f32_16x16x32_bf16 v[84:87], v[96:99], v[192:195], v[84:87]
	v_mfma_f32_16x16x32_bf16 v[108:111], v[96:99], v[200:203], v[108:111]
	v_mfma_f32_16x16x32_bf16 v[120:123], v[56:59], v[200:203], v[120:123]
	v_mfma_f32_16x16x32_bf16 v[136:139], v[56:59], v[226:229], v[136:139]
	v_mfma_f32_16x16x32_bf16 v[132:135], v[96:99], v[226:229], v[132:135]
	v_mfma_f32_16x16x32_bf16 v[100:103], v[96:99], v[234:237], v[100:103]
	v_mfma_f32_16x16x32_bf16 v[104:107], v[56:59], v[234:237], v[104:107]
	s_setprio 0
	s_setprio 1
	v_mfma_f32_16x16x32_bf16 v[160:163], v[124:127], v[164:167], v[160:163]
	v_mfma_f32_16x16x32_bf16 v[156:159], v[148:151], v[164:167], v[156:159]
	v_mfma_f32_16x16x32_bf16 v[140:143], v[148:151], v[196:199], v[140:143]
	v_mfma_f32_16x16x32_bf16 v[144:147], v[124:127], v[196:199], v[144:147]
	v_mfma_f32_16x16x32_bf16 v[116:119], v[124:127], v[222:225], v[116:119]
	v_mfma_f32_16x16x32_bf16 v[112:115], v[148:151], v[222:225], v[112:115]
	v_mfma_f32_16x16x32_bf16 v[76:79], v[148:151], v[230:233], v[76:79]
	v_mfma_f32_16x16x32_bf16 v[80:83], v[124:127], v[230:233], v[80:83]
	v_mfma_f32_16x16x32_bf16 v[160:163], v[128:131], v[192:195], v[160:163]
	v_mfma_f32_16x16x32_bf16 v[156:159], v[152:155], v[192:195], v[156:159]
	v_mfma_f32_16x16x32_bf16 v[140:143], v[152:155], v[200:203], v[140:143]
	v_mfma_f32_16x16x32_bf16 v[144:147], v[128:131], v[200:203], v[144:147]
	v_mfma_f32_16x16x32_bf16 v[116:119], v[128:131], v[226:229], v[116:119]
	v_mfma_f32_16x16x32_bf16 v[112:115], v[152:155], v[226:229], v[112:115]
	v_mfma_f32_16x16x32_bf16 v[76:79], v[152:155], v[234:237], v[76:79]
	v_mfma_f32_16x16x32_bf16 v[80:83], v[128:131], v[234:237], v[80:83]
	s_setprio 0
	s_barrier
	s_add_i32 s54, s54, s2
	v_lshl_add_u64 v[238:239], s[26:27], 0, v[184:185]
	s_mov_b32 m0, s54
	ds_read_b128 v[164:167], v220 offset:16384
	ds_read_b128 v[192:195], v220 offset:17408
	ds_read_b128 v[196:199], v220 offset:18432
	ds_read_b128 v[200:203], v220 offset:19456
	ds_read_b128 v[222:225], v220 offset:20480
	ds_read_b128 v[226:229], v220 offset:21504
	ds_read_b128 v[230:233], v220 offset:22528
	ds_read_b128 v[234:237], v220 offset:23552
	global_load_lds_dwordx4 v[238:239], off
	s_add_i32 m0, s54, 0x2000
	s_add_u32 vcc_lo, s26, 0x40000
	v_lshl_add_u64 v[240:241], s[26:27], 0, v[180:181]
	s_addc_u32 vcc_hi, s27, 0
	s_add_i32 s54, s55, s2
	global_load_lds_dwordx4 v[240:241], off
	v_lshl_add_u64 v[2:3], vcc, 0, v[184:185]
	s_mov_b32 m0, s54
	v_lshl_add_u64 v[242:243], s[28:29], 0, v[186:187]
	global_load_lds_dwordx4 v[2:3], off
	v_lshl_add_u64 v[2:3], vcc, 0, v[180:181]
	s_add_i32 m0, s54, 0x2000
	v_lshl_add_u64 v[244:245], s[28:29], 0, v[182:183]
	global_load_lds_dwordx4 v[2:3], off
	s_mov_b32 m0, s37
	s_nop 0
	global_load_lds_dwordx4 v[242:243], off
	s_mov_b32 m0, s38
	s_nop 0
	global_load_lds_dwordx4 v[244:245], off
	s_waitcnt vmcnt(8)
	s_waitcnt lgkmcnt(0)
	s_barrier
; #define PG8_STAGE(bufoff, gbase, voff) do { _Pragma("unroll") for (int _i = 0; _i < 2; ++_i) \
;         __builtin_amdgcn_global_load_lds((const unsigned*)((const char*)(gbase) + (voff)[_i]), (PG8_LAS unsigned*)(lds + (bufoff) + ldsw + _i * 8192), 16, 0, 0); } while (0)
; #define PG8_LDA(dst, b, h) do { _Pragma("unroll") for (int m = 0; m < 4; ++m) _Pragma("unroll") for (int k = 0; k < 2; ++k) dst[m][k] = *(const PG8_LAS bf16x8*)(lds + PG8_SA(b, h) + aoff + m * 2048 + k * 1024); } while (0)
; #define PG8_LDB(dst, b, h) do { _Pragma("unroll") for (int n = 0; n < 2; ++n) _Pragma("unroll") for (int k = 0; k < 2; ++k) dst[n][k] = *(const PG8_LAS bf16x8*)(lds + PG8_SB(b, h) + boff + n * 2048 + k * 1024); } while (0)
; #define PG8_MMA(ai, bj, At, Bt) do { __builtin_amdgcn_s_setprio(1); _Pragma("unroll") for (int m = 0; m < 4; ++m) _Pragma("unroll") for (int n = 0; n < 2; ++n) _Pragma("unroll") for (int k = 0; k < 2; ++k) \
;         acc[ai][bj][m][n] = __builtin_amdgcn_mfma_f32_16x16x32_bf16(Bt[n][k], At[m][k], acc[ai][bj][m][n], 0, 0, 0); __builtin_amdgcn_s_setprio(0); } while (0)
; #define PG8_WAIT_V(n) asm volatile("s_waitcnt vmcnt(" #n ")" ::: "memory")
; #define PG8_WAIT_L(n) asm volatile("s_waitcnt lgkmcnt(" #n ")" ::: "memory")
; #define PG8_BAR __builtin_amdgcn_s_barrier()
; #define PG8_SCHED __builtin_amdgcn_sched_barrier(0)
; template <class Epi, class Sched, bool ALIGN_EPI = false, bool SP2 = false>
; __device__ __forceinline__ void gemm_phase(PG8_LAS unsigned char* lds, const Gemm g, const Sched& S, const Epi& E) {
;     ...
;             PG8_WAIT_V(8); PG8_WAIT_L(0); PG8_BAR; PG8_MMA(1, 0, At, B0); PG8_MMA(1, 1, At, B1); PG8_BAR; PG8_SCHED;
;             PG8_LDB(B0, 1, 0); PG8_LDB(B1, 1, 1); PG8_SCHED; PG8_LDA(At, 1, 0); PG8_STAGE(PG8_SA(0, 1), a2 + hstep, voffA);
;             PG8_WAIT_V(8); PG8_WAIT_L(0); PG8_BAR; PG8_MMA(0, 0, At, B0); PG8_MMA(0, 1, At, B1); PG8_BAR; PG8_SCHED;
;             PG8_LDA(At, 1, 1); PG8_STAGE(PG8_SB(1, 0), b3, voffB); PG8_STAGE(PG8_SB(1, 1), b3 + hstep, voffB); PG8_STAGE(PG8_SA(1, 0), a3, voffA);
	s_setprio 1
	s_waitcnt lgkmcnt(0)
	v_mfma_f32_16x16x32_bf16 v[72:75], v[52:55], v[164:167], v[72:75]
	v_mfma_f32_16x16x32_bf16 v[68:71], v[92:95], v[164:167], v[68:71]
	v_mfma_f32_16x16x32_bf16 v[44:47], v[92:95], v[196:199], v[44:47]
	v_mfma_f32_16x16x32_bf16 v[48:51], v[52:55], v[196:199], v[48:51]
	v_mfma_f32_16x16x32_bf16 v[32:35], v[52:55], v[222:225], v[32:35]
	v_mfma_f32_16x16x32_bf16 v[28:31], v[92:95], v[222:225], v[28:31]
	v_mfma_f32_16x16x32_bf16 v[12:15], v[92:95], v[230:233], v[12:15]
	v_mfma_f32_16x16x32_bf16 v[16:19], v[52:55], v[230:233], v[16:19]
	v_mfma_f32_16x16x32_bf16 v[72:75], v[56:59], v[192:195], v[72:75]
	v_mfma_f32_16x16x32_bf16 v[68:71], v[96:99], v[192:195], v[68:71]
	v_mfma_f32_16x16x32_bf16 v[44:47], v[96:99], v[200:203], v[44:47]
	v_mfma_f32_16x16x32_bf16 v[48:51], v[56:59], v[200:203], v[48:51]
	v_mfma_f32_16x16x32_bf16 v[32:35], v[56:59], v[226:229], v[32:35]
	v_mfma_f32_16x16x32_bf16 v[28:31], v[96:99], v[226:229], v[28:31]
	v_mfma_f32_16x16x32_bf16 v[12:15], v[96:99], v[234:237], v[12:15]
	v_mfma_f32_16x16x32_bf16 v[16:19], v[56:59], v[234:237], v[16:19]
	s_setprio 0
	s_setprio 1
	v_mfma_f32_16x16x32_bf16 v[40:43], v[124:127], v[196:199], v[40:43]
	v_mfma_f32_16x16x32_bf16 v[36:39], v[148:151], v[196:199], v[36:39]
	v_mfma_f32_16x16x32_bf16 v[20:23], v[148:151], v[222:225], v[20:23]
	v_mfma_f32_16x16x32_bf16 v[24:27], v[124:127], v[222:225], v[24:27]
	v_mfma_f32_16x16x32_bf16 v[8:11], v[124:127], v[230:233], v[8:11]
	v_mfma_f32_16x16x32_bf16 v[2:5], v[148:151], v[230:233], v[4:7]
	v_mfma_f32_16x16x32_bf16 v[56:59], v[148:151], v[164:167], v[60:63]
	v_mfma_f32_16x16x32_bf16 v[52:55], v[124:127], v[164:167], v[64:67]
	v_mfma_f32_16x16x32_bf16 v[40:43], v[128:131], v[200:203], v[40:43]
	v_mfma_f32_16x16x32_bf16 v[36:39], v[152:155], v[200:203], v[36:39]
	v_mfma_f32_16x16x32_bf16 v[20:23], v[152:155], v[226:229], v[20:23]
	v_mfma_f32_16x16x32_bf16 v[24:27], v[128:131], v[226:229], v[24:27]
	v_mfma_f32_16x16x32_bf16 v[8:11], v[128:131], v[234:237], v[8:11]
	v_mfma_f32_16x16x32_bf16 v[2:5], v[152:155], v[234:237], v[2:5]
	v_mfma_f32_16x16x32_bf16 v[56:59], v[152:155], v[192:195], v[56:59]
	v_mfma_f32_16x16x32_bf16 v[52:55], v[128:131], v[192:195], v[52:55]
	s_setprio 0
	s_barrier
	s_add_i32 s54, 0, 0x18000
	v_add_u32_e32 v0, s54, v218
	s_add_i32 s55, 0, 0x1c000
	ds_read_b128 v[60:63], v0
	ds_read_b128 v[64:67], v0 offset:1024
	ds_read_b128 v[92:95], v0 offset:2048
	ds_read_b128 v[96:99], v0 offset:3072
	v_add_u32_e32 v0, s55, v218
	ds_read_b128 v[124:127], v0
	ds_read_b128 v[128:131], v0 offset:1024
	ds_read_b128 v[148:151], v0 offset:2048
	ds_read_b128 v[152:155], v0 offset:3072
	s_add_u32 s28, s28, 0x40000
	s_addc_u32 s29, s29, 0
	s_mov_b32 m0, s39
	v_lshl_add_u64 v[6:7], s[28:29], 0, v[186:187]
	ds_read_b128 v[164:167], v220 offset:32768
	ds_read_b128 v[192:195], v220 offset:33792
	ds_read_b128 v[196:199], v220 offset:34816
	ds_read_b128 v[200:203], v220 offset:35840
	ds_read_b128 v[222:225], v220 offset:36864
	ds_read_b128 v[226:229], v220 offset:37888
	ds_read_b128 v[230:233], v220 offset:38912
	ds_read_b128 v[234:237], v220 offset:39936
	global_load_lds_dwordx4 v[6:7], off
	v_lshl_add_u64 v[6:7], s[28:29], 0, v[182:183]
	s_mov_b32 m0, s44
	s_nop 0
	global_load_lds_dwordx4 v[6:7], off
	s_waitcnt vmcnt(8)
	s_waitcnt lgkmcnt(0)
	s_barrier
	s_setprio 1
	s_waitcnt lgkmcnt(0)
	v_mfma_f32_16x16x32_bf16 v[88:91], v[60:63], v[164:167], v[88:91]
	v_mfma_f32_16x16x32_bf16 v[84:87], v[92:95], v[164:167], v[84:87]
	v_mfma_f32_16x16x32_bf16 v[108:111], v[92:95], v[196:199], v[108:111]
	v_mfma_f32_16x16x32_bf16 v[120:123], v[60:63], v[196:199], v[120:123]
	v_mfma_f32_16x16x32_bf16 v[136:139], v[60:63], v[222:225], v[136:139]
	v_mfma_f32_16x16x32_bf16 v[132:135], v[92:95], v[222:225], v[132:135]
	v_mfma_f32_16x16x32_bf16 v[100:103], v[92:95], v[230:233], v[100:103]
	v_mfma_f32_16x16x32_bf16 v[104:107], v[60:63], v[230:233], v[104:107]
	v_mfma_f32_16x16x32_bf16 v[88:91], v[64:67], v[192:195], v[88:91]
	v_mfma_f32_16x16x32_bf16 v[84:87], v[96:99], v[192:195], v[84:87]
	v_mfma_f32_16x16x32_bf16 v[108:111], v[96:99], v[200:203], v[108:111]
	v_mfma_f32_16x16x32_bf16 v[120:123], v[64:67], v[200:203], v[120:123]
	v_mfma_f32_16x16x32_bf16 v[136:139], v[64:67], v[226:229], v[136:139]
	v_mfma_f32_16x16x32_bf16 v[132:135], v[96:99], v[226:229], v[132:135]
	v_mfma_f32_16x16x32_bf16 v[100:103], v[96:99], v[234:237], v[100:103]
	v_mfma_f32_16x16x32_bf16 v[104:107], v[64:67], v[234:237], v[104:107]
	s_setprio 0
	s_setprio 1
	v_mfma_f32_16x16x32_bf16 v[160:163], v[124:127], v[164:167], v[160:163]
	v_mfma_f32_16x16x32_bf16 v[156:159], v[148:151], v[164:167], v[156:159]
	v_mfma_f32_16x16x32_bf16 v[140:143], v[148:151], v[196:199], v[140:143]
	v_mfma_f32_16x16x32_bf16 v[144:147], v[124:127], v[196:199], v[144:147]
	v_mfma_f32_16x16x32_bf16 v[116:119], v[124:127], v[222:225], v[116:119]
	v_mfma_f32_16x16x32_bf16 v[112:115], v[148:151], v[222:225], v[112:115]
	v_mfma_f32_16x16x32_bf16 v[76:79], v[148:151], v[230:233], v[76:79]
	v_mfma_f32_16x16x32_bf16 v[80:83], v[124:127], v[230:233], v[80:83]
	v_mfma_f32_16x16x32_bf16 v[160:163], v[128:131], v[192:195], v[160:163]
	v_mfma_f32_16x16x32_bf16 v[156:159], v[152:155], v[192:195], v[156:159]
	v_mfma_f32_16x16x32_bf16 v[140:143], v[152:155], v[200:203], v[140:143]
	v_mfma_f32_16x16x32_bf16 v[144:147], v[128:131], v[200:203], v[144:147]
	v_mfma_f32_16x16x32_bf16 v[116:119], v[128:131], v[226:229], v[116:119]
	v_mfma_f32_16x16x32_bf16 v[112:115], v[152:155], v[226:229], v[112:115]
	v_mfma_f32_16x16x32_bf16 v[76:79], v[152:155], v[234:237], v[76:79]
	v_mfma_f32_16x16x32_bf16 v[80:83], v[128:131], v[234:237], v[80:83]
	s_setprio 0
	s_barrier
; #define PG8_STAGE(bufoff, gbase, voff) do { _Pragma("unroll") for (int _i = 0; _i < 2; ++_i) \
;         __builtin_amdgcn_global_load_lds((const unsigned*)((const char*)(gbase) + (voff)[_i]), (PG8_LAS unsigned*)(lds + (bufoff) + ldsw + _i * 8192), 16, 0, 0); } while (0)
; #define PG8_LDA(dst, b, h) do { _Pragma("unroll") for (int m = 0; m < 4; ++m) _Pragma("unroll") for (int k = 0; k < 2; ++k) dst[m][k] = *(const PG8_LAS bf16x8*)(lds + PG8_SA(b, h) + aoff + m * 2048 + k * 1024); } while (0)
; #define PG8_MMA(ai, bj, At, Bt) do { __builtin_amdgcn_s_setprio(1); _Pragma("unroll") for (int m = 0; m < 4; ++m) _Pragma("unroll") for (int n = 0; n < 2; ++n) _Pragma("unroll") for (int k = 0; k < 2; ++k) \
;         acc[ai][bj][m][n] = __builtin_amdgcn_mfma_f32_16x16x32_bf16(Bt[n][k], At[m][k], acc[ai][bj][m][n], 0, 0, 0); __builtin_amdgcn_s_setprio(0); } while (0)
; #define PG8_WAIT_V(n) asm volatile("s_waitcnt vmcnt(" #n ")" ::: "memory")
; #define PG8_WAIT_L(n) asm volatile("s_waitcnt lgkmcnt(" #n ")" ::: "memory")
; #define PG8_BAR __builtin_amdgcn_s_barrier()
; #define PG8_SCHED __builtin_amdgcn_sched_barrier(0)
; template <class Epi, class Sched, bool ALIGN_EPI = false, bool SP2 = false>
; __device__ __forceinline__ void gemm_phase(PG8_LAS unsigned char* lds, const Gemm g, const Sched& S, const Epi& E) {
;     ...
;             PG8_LDA(At, 1, 1); PG8_STAGE(PG8_SB(1, 0), b3, voffB); PG8_STAGE(PG8_SB(1, 1), b3 + hstep, voffB); PG8_STAGE(PG8_SA(1, 0), a3, voffA);
;             PG8_WAIT_V(8); PG8_WAIT_L(0); PG8_BAR; PG8_MMA(1, 0, At, B0); PG8_MMA(1, 1, At, B1); PG8_BAR; PG8_SCHED;
	s_add_i32 s28, s54, s2
	v_lshl_add_u64 v[6:7], v[238:239], 0, s[34:35]
	s_mov_b32 m0, s28
	ds_read_b128 v[164:167], v220 offset:49152
	ds_read_b128 v[192:195], v220 offset:50176
	ds_read_b128 v[196:199], v220 offset:51200
	ds_read_b128 v[200:203], v220 offset:52224
	ds_read_b128 v[222:225], v220 offset:53248
	ds_read_b128 v[226:229], v220 offset:54272
	ds_read_b128 v[230:233], v220 offset:55296
	ds_read_b128 v[234:237], v220 offset:56320
	global_load_lds_dwordx4 v[6:7], off
	s_add_i32 m0, s28, 0x2000
	s_add_u32 s26, s26, 0x40080
	v_lshl_add_u64 v[6:7], v[240:241], 0, s[34:35]
	s_addc_u32 s27, s27, 0
	s_add_i32 s28, s55, s2
	global_load_lds_dwordx4 v[6:7], off
	v_lshl_add_u64 v[6:7], s[26:27], 0, v[184:185]
	s_mov_b32 m0, s28
	s_nop 0
	global_load_lds_dwordx4 v[6:7], off
	v_lshl_add_u64 v[6:7], s[26:27], 0, v[180:181]
	s_add_i32 m0, s28, 0x2000
	s_nop 0
	global_load_lds_dwordx4 v[6:7], off
	v_lshl_add_u64 v[6:7], v[242:243], 0, s[34:35]
	s_mov_b32 m0, s47
	s_nop 0
	global_load_lds_dwordx4 v[6:7], off
	v_lshl_add_u64 v[6:7], v[244:245], 0, s[34:35]
	s_mov_b32 m0, s48
	s_nop 0
	global_load_lds_dwordx4 v[6:7], off
	s_waitcnt vmcnt(8)
	s_waitcnt lgkmcnt(0)
	s_barrier
	s_setprio 1
	s_waitcnt lgkmcnt(0)
	v_mfma_f32_16x16x32_bf16 v[72:75], v[60:63], v[164:167], v[72:75]
	v_mfma_f32_16x16x32_bf16 v[68:71], v[92:95], v[164:167], v[68:71]
	v_mfma_f32_16x16x32_bf16 v[44:47], v[92:95], v[196:199], v[44:47]
	v_mfma_f32_16x16x32_bf16 v[48:51], v[60:63], v[196:199], v[48:51]
	v_mfma_f32_16x16x32_bf16 v[32:35], v[60:63], v[222:225], v[32:35]
	v_mfma_f32_16x16x32_bf16 v[28:31], v[92:95], v[222:225], v[28:31]
	v_mfma_f32_16x16x32_bf16 v[12:15], v[92:95], v[230:233], v[12:15]
	v_mfma_f32_16x16x32_bf16 v[16:19], v[60:63], v[230:233], v[16:19]
	v_mfma_f32_16x16x32_bf16 v[72:75], v[64:67], v[192:195], v[72:75]
	v_mfma_f32_16x16x32_bf16 v[68:71], v[96:99], v[192:195], v[68:71]
	v_mfma_f32_16x16x32_bf16 v[44:47], v[96:99], v[200:203], v[44:47]
	v_mfma_f32_16x16x32_bf16 v[48:51], v[64:67], v[200:203], v[48:51]
	v_mfma_f32_16x16x32_bf16 v[32:35], v[64:67], v[226:229], v[32:35]
	v_mfma_f32_16x16x32_bf16 v[28:31], v[96:99], v[226:229], v[28:31]
	v_mfma_f32_16x16x32_bf16 v[12:15], v[96:99], v[234:237], v[12:15]
	v_mfma_f32_16x16x32_bf16 v[16:19], v[64:67], v[234:237], v[16:19]
	s_setprio 0
	s_setprio 1
	v_mfma_f32_16x16x32_bf16 v[52:55], v[124:127], v[164:167], v[52:55]
	v_mfma_f32_16x16x32_bf16 v[64:67], v[128:131], v[192:195], v[52:55]
	v_mfma_f32_16x16x32_bf16 v[40:43], v[124:127], v[196:199], v[40:43]
	v_mfma_f32_16x16x32_bf16 v[52:55], v[148:151], v[164:167], v[56:59]
	v_mfma_f32_16x16x32_bf16 v[36:39], v[148:151], v[196:199], v[36:39]
	v_mfma_f32_16x16x32_bf16 v[24:27], v[124:127], v[222:225], v[24:27]
	v_mfma_f32_16x16x32_bf16 v[6:9], v[124:127], v[230:233], v[8:11]
	v_mfma_f32_16x16x32_bf16 v[20:23], v[148:151], v[222:225], v[20:23]
	v_mfma_f32_16x16x32_bf16 v[2:5], v[148:151], v[230:233], v[2:5]
	v_mfma_f32_16x16x32_bf16 v[60:63], v[152:155], v[192:195], v[52:55]
	v_mfma_f32_16x16x32_bf16 v[36:39], v[152:155], v[200:203], v[36:39]
	v_mfma_f32_16x16x32_bf16 v[40:43], v[128:131], v[200:203], v[40:43]
	v_mfma_f32_16x16x32_bf16 v[24:27], v[128:131], v[226:229], v[24:27]
	v_mfma_f32_16x16x32_bf16 v[20:23], v[152:155], v[226:229], v[20:23]
	v_mfma_f32_16x16x32_bf16 v[4:7], v[152:155], v[234:237], v[2:5]
	v_mfma_f32_16x16x32_bf16 v[8:11], v[128:131], v[234:237], v[6:9]
	s_setprio 0
	s_barrier
	s_add_i32 s78, s78, 2
	s_add_u32 s16, s16, 0x100
	s_addc_u32 s17, s17, 0
	s_add_u32 s73, s73, 0x100
	s_addc_u32 s77, s77, 0
	s_cmp_gt_u32 s78, 13
	s_cbranch_scc0 .LBB0_429
	s_and_b64 vcc, exec, s[6:7]
	s_cbranch_vccz .LBB0_432
	s_barrier

; #define PG8_STAGE(bufoff, gbase, voff) do { _Pragma("unroll") for (int _i = 0; _i < 2; ++_i) \
;         __builtin_amdgcn_global_load_lds((const unsigned*)((const char*)(gbase) + (voff)[_i]), (PG8_LAS unsigned*)(lds + (bufoff) + ldsw + _i * 8192), 16, 0, 0); } while (0)
; #define PG8_LDA(dst, b, h) do { _Pragma("unroll") for (int m = 0; m < 4; ++m) _Pragma("unroll") for (int k = 0; k < 2; ++k) dst[m][k] = *(const PG8_LAS bf16x8*)(lds + PG8_SA(b, h) + aoff + m * 2048 + k * 1024); } while (0)
; #define PG8_LDB(dst, b, h) do { _Pragma("unroll") for (int n = 0; n < 2; ++n) _Pragma("unroll") for (int k = 0; k < 2; ++k) dst[n][k] = *(const PG8_LAS bf16x8*)(lds + PG8_SB(b, h) + boff + n * 2048 + k * 1024); } while (0)
; #define PG8_MMA(ai, bj, At, Bt) do { __builtin_amdgcn_s_setprio(1); _Pragma("unroll") for (int m = 0; m < 4; ++m) _Pragma("unroll") for (int n = 0; n < 2; ++n) _Pragma("unroll") for (int k = 0; k < 2; ++k) \
;         acc[ai][bj][m][n] = __builtin_amdgcn_mfma_f32_16x16x32_bf16(Bt[n][k], At[m][k], acc[ai][bj][m][n], 0, 0, 0); __builtin_amdgcn_s_setprio(0); } while (0)
; #define PG8_WAIT_V(n) asm volatile("s_waitcnt vmcnt(" #n ")" ::: "memory")
; #define PG8_BAR __builtin_amdgcn_s_barrier()
; template <class Epi, class Sched, bool ALIGN_EPI = false, bool SP2 = false>
; __device__ __forceinline__ void gemm_phase(PG8_LAS unsigned char* lds, const Gemm g, const Sched& S, const Epi& E) {
;     ...
;         for (int t = 0; t < nt; t += 2) {
;             const bool last = (t == nt - 2);
;             const char* a1 = cA + (size_t)(t + 1) * kstep;
;             const char* a2 = last ? nA : cA + (size_t)(t + 2) * kstep; const char* b2 = last ? nB : cB + (size_t)(t + 2) * kstep;
;             const char* a3 = a2 + kstep; const char* b3 = b2 + kstep;
;             if (last && has_next) S.a_ready(nxt);
;             if constexpr (SP2) {
;             PG8_LDB(B0, 0, 0); PG8_LDB(B1, 0, 1); PG8_SCHED; PG8_LDA(At, 0, 0); PG8_STAGE(PG8_SA(1, 1), a1 + hstep, voffA);
;             PG8_WAIT_V(8); PG8_WAIT_L(0); PG8_BAR; PG8_MMA(0, 0, At, B0); PG8_MMA(0, 1, At, B1); PG8_BAR; PG8_SCHED;
;             PG8_LDA(At, 0, 1); PG8_STAGE(PG8_SB(0, 0), b2, voffB); PG8_STAGE(PG8_SB(0, 1), b2 + hstep, voffB); PG8_STAGE(PG8_SA(0, 0), a2, voffA);
;             PG8_WAIT_V(8); PG8_WAIT_L(0); PG8_BAR; PG8_MMA(1, 0, At, B0); PG8_MMA(1, 1, At, B1); PG8_BAR; PG8_SCHED;
.LBB0_553:
	s_add_u32 s26, s16, 0xfff80080
	s_addc_u32 s27, s17, -1
	s_add_i32 s54, 0, 0x10000
	s_cmp_eq_u32 vcc_hi, 28
	s_cselect_b32 s29, s23, s27
	s_cselect_b32 s28, s38, s26
	s_cselect_b32 s27, s21, vcc_lo
	s_cselect_b32 s26, s39, s78
	s_add_i32 s80, 0, 0x14000
	v_add_u32_e32 v134, s54, v191
	v_add_u32_e32 v166, s80, v191
	ds_read_b128 v[114:117], v134
	ds_read_b128 v[118:121], v134 offset:1024
	ds_read_b128 v[122:125], v134 offset:2048
	ds_read_b128 v[134:137], v134 offset:3072
	ds_read_b128 v[146:149], v166
	ds_read_b128 v[150:153], v166 offset:1024
	ds_read_b128 v[180:183], v166 offset:2048
	ds_read_b128 v[184:187], v166 offset:3072
	v_lshl_add_u64 v[166:167], s[16:17], 0, v[162:163]
	s_add_i32 m0, s48, 0xc000
	ds_read_b128 v[196:199], v194
	ds_read_b128 v[200:203], v194 offset:1024
	ds_read_b128 v[218:221], v194 offset:2048
	ds_read_b128 v[222:225], v194 offset:3072
	ds_read_b128 v[226:229], v194 offset:4096
	ds_read_b128 v[230:233], v194 offset:5120
	ds_read_b128 v[234:237], v194 offset:6144
	ds_read_b128 v[238:241], v194 offset:7168
	global_load_lds_dwordx4 v[166:167], off
	v_lshl_add_u64 v[166:167], s[16:17], 0, v[164:165]
	s_add_i32 m0, s48, 0xe000
	s_nop 0
	global_load_lds_dwordx4 v[166:167], off
	s_waitcnt vmcnt(8)
	s_waitcnt lgkmcnt(0)
	s_barrier
	s_setprio 1
	s_waitcnt lgkmcnt(0)
	v_mfma_f32_16x16x32_bf16 v[142:145], v[114:117], v[196:199], v[142:145]
	v_mfma_f32_16x16x32_bf16 v[138:141], v[122:125], v[196:199], v[138:141]
	v_mfma_f32_16x16x32_bf16 v[106:109], v[122:125], v[218:221], v[106:109]
	v_mfma_f32_16x16x32_bf16 v[110:113], v[114:117], v[218:221], v[110:113]
	v_mfma_f32_16x16x32_bf16 v[94:97], v[114:117], v[226:229], v[94:97]
	v_mfma_f32_16x16x32_bf16 v[90:93], v[122:125], v[226:229], v[90:93]
	v_mfma_f32_16x16x32_bf16 v[74:77], v[122:125], v[234:237], v[74:77]
	v_mfma_f32_16x16x32_bf16 v[78:81], v[114:117], v[234:237], v[78:81]
	v_mfma_f32_16x16x32_bf16 v[142:145], v[118:121], v[200:203], v[142:145]
	v_mfma_f32_16x16x32_bf16 v[138:141], v[134:137], v[200:203], v[138:141]
	v_mfma_f32_16x16x32_bf16 v[106:109], v[134:137], v[222:225], v[106:109]
	v_mfma_f32_16x16x32_bf16 v[110:113], v[118:121], v[222:225], v[110:113]
	v_mfma_f32_16x16x32_bf16 v[94:97], v[118:121], v[230:233], v[94:97]
	v_mfma_f32_16x16x32_bf16 v[90:93], v[134:137], v[230:233], v[90:93]
	v_mfma_f32_16x16x32_bf16 v[74:77], v[134:137], v[238:241], v[74:77]
	v_mfma_f32_16x16x32_bf16 v[78:81], v[118:121], v[238:241], v[78:81]
	s_setprio 0
	s_setprio 1
	v_mfma_f32_16x16x32_bf16 v[130:133], v[146:149], v[196:199], v[130:133]
	v_mfma_f32_16x16x32_bf16 v[126:129], v[180:183], v[196:199], v[126:129]
	v_mfma_f32_16x16x32_bf16 v[98:101], v[180:183], v[218:221], v[98:101]
	v_mfma_f32_16x16x32_bf16 v[102:105], v[146:149], v[218:221], v[102:105]
	v_mfma_f32_16x16x32_bf16 v[86:89], v[146:149], v[226:229], v[86:89]
	v_mfma_f32_16x16x32_bf16 v[82:85], v[180:183], v[226:229], v[82:85]
	v_mfma_f32_16x16x32_bf16 v[66:69], v[180:183], v[234:237], v[66:69]
	v_mfma_f32_16x16x32_bf16 v[70:73], v[146:149], v[234:237], v[70:73]
	v_mfma_f32_16x16x32_bf16 v[130:133], v[150:153], v[200:203], v[130:133]
	v_mfma_f32_16x16x32_bf16 v[126:129], v[184:187], v[200:203], v[126:129]
	v_mfma_f32_16x16x32_bf16 v[98:101], v[184:187], v[222:225], v[98:101]
	v_mfma_f32_16x16x32_bf16 v[102:105], v[150:153], v[222:225], v[102:105]
	v_mfma_f32_16x16x32_bf16 v[86:89], v[150:153], v[230:233], v[86:89]
	v_mfma_f32_16x16x32_bf16 v[82:85], v[184:187], v[230:233], v[82:85]
	v_mfma_f32_16x16x32_bf16 v[66:69], v[184:187], v[238:241], v[66:69]
	v_mfma_f32_16x16x32_bf16 v[70:73], v[150:153], v[238:241], v[70:73]
	s_setprio 0
	s_barrier
	s_add_i32 s54, s54, s2
	v_lshl_add_u64 v[166:167], s[26:27], 0, v[0:1]
	s_mov_b32 m0, s54
	ds_read_b128 v[196:199], v194 offset:16384
	ds_read_b128 v[200:203], v194 offset:17408
	ds_read_b128 v[218:221], v194 offset:18432
	ds_read_b128 v[222:225], v194 offset:19456
	ds_read_b128 v[226:229], v194 offset:20480
	ds_read_b128 v[230:233], v194 offset:21504
	ds_read_b128 v[234:237], v194 offset:22528
	ds_read_b128 v[238:241], v194 offset:23552
	global_load_lds_dwordx4 v[166:167], off
	s_add_i32 m0, s54, 0x2000
	s_add_u32 s54, s26, 0x80000
	v_lshl_add_u64 v[188:189], s[26:27], 0, v[154:155]
	s_addc_u32 s55, s27, 0
	s_add_i32 s80, s80, s2
	global_load_lds_dwordx4 v[188:189], off
	v_lshl_add_u64 v[242:243], s[54:55], 0, v[0:1]
	s_mov_b32 m0, s80
	v_lshl_add_u64 v[244:245], s[28:29], 0, v[156:157]
	global_load_lds_dwordx4 v[242:243], off
	v_lshl_add_u64 v[242:243], s[54:55], 0, v[154:155]
	s_add_i32 m0, s80, 0x2000
	s_nop 0
	global_load_lds_dwordx4 v[242:243], off
	v_lshl_add_u64 v[242:243], s[28:29], 0, v[158:159]
	s_mov_b32 m0, s48
	s_nop 0
	global_load_lds_dwordx4 v[242:243], off
	s_mov_b32 m0, s49
	s_nop 0
	global_load_lds_dwordx4 v[244:245], off
	s_waitcnt vmcnt(8)
	s_waitcnt lgkmcnt(0)
	s_barrier
; #define PG8_STAGE(bufoff, gbase, voff) do { _Pragma("unroll") for (int _i = 0; _i < 2; ++_i) \
;         __builtin_amdgcn_global_load_lds((const unsigned*)((const char*)(gbase) + (voff)[_i]), (PG8_LAS unsigned*)(lds + (bufoff) + ldsw + _i * 8192), 16, 0, 0); } while (0)
; #define PG8_LDA(dst, b, h) do { _Pragma("unroll") for (int m = 0; m < 4; ++m) _Pragma("unroll") for (int k = 0; k < 2; ++k) dst[m][k] = *(const PG8_LAS bf16x8*)(lds + PG8_SA(b, h) + aoff + m * 2048 + k * 1024); } while (0)
; #define PG8_LDB(dst, b, h) do { _Pragma("unroll") for (int n = 0; n < 2; ++n) _Pragma("unroll") for (int k = 0; k < 2; ++k) dst[n][k] = *(const PG8_LAS bf16x8*)(lds + PG8_SB(b, h) + boff + n * 2048 + k * 1024); } while (0)
; #define PG8_MMA(ai, bj, At, Bt) do { __builtin_amdgcn_s_setprio(1); _Pragma("unroll") for (int m = 0; m < 4; ++m) _Pragma("unroll") for (int n = 0; n < 2; ++n) _Pragma("unroll") for (int k = 0; k < 2; ++k) \
;         acc[ai][bj][m][n] = __builtin_amdgcn_mfma_f32_16x16x32_bf16(Bt[n][k], At[m][k], acc[ai][bj][m][n], 0, 0, 0); __builtin_amdgcn_s_setprio(0); } while (0)
; #define PG8_WAIT_V(n) asm volatile("s_waitcnt vmcnt(" #n ")" ::: "memory")
; #define PG8_WAIT_L(n) asm volatile("s_waitcnt lgkmcnt(" #n ")" ::: "memory")
; #define PG8_BAR __builtin_amdgcn_s_barrier()
; #define PG8_SCHED __builtin_amdgcn_sched_barrier(0)
; template <class Epi, class Sched, bool ALIGN_EPI = false, bool SP2 = false>
; __device__ __forceinline__ void gemm_phase(PG8_LAS unsigned char* lds, const Gemm g, const Sched& S, const Epi& E) {
;     ...
;             PG8_WAIT_V(8); PG8_WAIT_L(0); PG8_BAR; PG8_MMA(1, 0, At, B0); PG8_MMA(1, 1, At, B1); PG8_BAR; PG8_SCHED;
;             PG8_LDB(B0, 1, 0); PG8_LDB(B1, 1, 1); PG8_SCHED; PG8_LDA(At, 1, 0); PG8_STAGE(PG8_SA(0, 1), a2 + hstep, voffA);
;             PG8_WAIT_V(8); PG8_WAIT_L(0); PG8_BAR; PG8_MMA(0, 0, At, B0); PG8_MMA(0, 1, At, B1); PG8_BAR; PG8_SCHED;
;             PG8_LDA(At, 1, 1); PG8_STAGE(PG8_SB(1, 0), b3, voffB); PG8_STAGE(PG8_SB(1, 1), b3 + hstep, voffB); PG8_STAGE(PG8_SA(1, 0), a3, voffA);
	s_setprio 1
	s_waitcnt lgkmcnt(0)
	v_mfma_f32_16x16x32_bf16 v[62:65], v[114:117], v[196:199], v[62:65]
	v_mfma_f32_16x16x32_bf16 v[58:61], v[122:125], v[196:199], v[58:61]
	v_mfma_f32_16x16x32_bf16 v[42:45], v[122:125], v[218:221], v[42:45]
	v_mfma_f32_16x16x32_bf16 v[46:49], v[114:117], v[218:221], v[46:49]
	v_mfma_f32_16x16x32_bf16 v[30:33], v[114:117], v[226:229], v[30:33]
	v_mfma_f32_16x16x32_bf16 v[26:29], v[122:125], v[226:229], v[26:29]
	v_mfma_f32_16x16x32_bf16 v[10:13], v[122:125], v[234:237], v[10:13]
	v_mfma_f32_16x16x32_bf16 v[14:17], v[114:117], v[234:237], v[14:17]
	v_mfma_f32_16x16x32_bf16 v[62:65], v[118:121], v[200:203], v[62:65]
	v_mfma_f32_16x16x32_bf16 v[58:61], v[134:137], v[200:203], v[58:61]
	v_mfma_f32_16x16x32_bf16 v[42:45], v[134:137], v[222:225], v[42:45]
	v_mfma_f32_16x16x32_bf16 v[46:49], v[118:121], v[222:225], v[46:49]
	v_mfma_f32_16x16x32_bf16 v[30:33], v[118:121], v[230:233], v[30:33]
	v_mfma_f32_16x16x32_bf16 v[26:29], v[134:137], v[230:233], v[26:29]
	v_mfma_f32_16x16x32_bf16 v[10:13], v[134:137], v[238:241], v[10:13]
	v_mfma_f32_16x16x32_bf16 v[14:17], v[118:121], v[238:241], v[14:17]
	s_setprio 0
	s_setprio 1
	v_mfma_f32_16x16x32_bf16 v[54:57], v[146:149], v[196:199], v[54:57]
	v_mfma_f32_16x16x32_bf16 v[50:53], v[180:183], v[196:199], v[50:53]
	v_mfma_f32_16x16x32_bf16 v[34:37], v[180:183], v[218:221], v[34:37]
	v_mfma_f32_16x16x32_bf16 v[38:41], v[146:149], v[218:221], v[38:41]
	v_mfma_f32_16x16x32_bf16 v[22:25], v[146:149], v[226:229], v[22:25]
	v_mfma_f32_16x16x32_bf16 v[18:21], v[180:183], v[226:229], v[18:21]
	v_mfma_f32_16x16x32_bf16 v[2:5], v[180:183], v[234:237], v[2:5]
	v_mfma_f32_16x16x32_bf16 v[6:9], v[146:149], v[234:237], v[6:9]
	v_mfma_f32_16x16x32_bf16 v[54:57], v[150:153], v[200:203], v[54:57]
	v_mfma_f32_16x16x32_bf16 v[50:53], v[184:187], v[200:203], v[50:53]
	v_mfma_f32_16x16x32_bf16 v[34:37], v[184:187], v[222:225], v[34:37]
	v_mfma_f32_16x16x32_bf16 v[38:41], v[150:153], v[222:225], v[38:41]
	v_mfma_f32_16x16x32_bf16 v[22:25], v[150:153], v[230:233], v[22:25]
	v_mfma_f32_16x16x32_bf16 v[18:21], v[184:187], v[230:233], v[18:21]
	v_mfma_f32_16x16x32_bf16 v[2:5], v[184:187], v[238:241], v[2:5]
	v_mfma_f32_16x16x32_bf16 v[6:9], v[150:153], v[238:241], v[6:9]
	s_setprio 0
	s_barrier
	s_add_i32 s54, 0, 0x18000
	s_add_i32 s55, 0, 0x1c000
	v_add_u32_e32 v134, s54, v191
	v_add_u32_e32 v184, s55, v191
	ds_read_b128 v[114:117], v134
	ds_read_b128 v[118:121], v134 offset:1024
	ds_read_b128 v[122:125], v134 offset:2048
	ds_read_b128 v[134:137], v134 offset:3072
	ds_read_b128 v[146:149], v184
	ds_read_b128 v[150:153], v184 offset:1024
	ds_read_b128 v[180:183], v184 offset:2048
	ds_read_b128 v[184:187], v184 offset:3072
	s_add_u32 s28, s28, 0x80000
	s_addc_u32 s29, s29, 0
	s_mov_b32 m0, s50
	v_lshl_add_u64 v[246:247], s[28:29], 0, v[158:159]
	ds_read_b128 v[196:199], v194 offset:32768
	ds_read_b128 v[200:203], v194 offset:33792
	ds_read_b128 v[218:221], v194 offset:34816
	ds_read_b128 v[222:225], v194 offset:35840
	ds_read_b128 v[226:229], v194 offset:36864
	ds_read_b128 v[230:233], v194 offset:37888
	ds_read_b128 v[234:237], v194 offset:38912
	ds_read_b128 v[238:241], v194 offset:39936
	global_load_lds_dwordx4 v[246:247], off
	v_lshl_add_u64 v[246:247], s[28:29], 0, v[156:157]
	s_mov_b32 m0, s51
	s_nop 0
	global_load_lds_dwordx4 v[246:247], off
	s_waitcnt vmcnt(8)
	s_waitcnt lgkmcnt(0)
	s_barrier
	s_setprio 1
	s_waitcnt lgkmcnt(0)
	v_mfma_f32_16x16x32_bf16 v[142:145], v[114:117], v[196:199], v[142:145]
	v_mfma_f32_16x16x32_bf16 v[138:141], v[122:125], v[196:199], v[138:141]
	v_mfma_f32_16x16x32_bf16 v[106:109], v[122:125], v[218:221], v[106:109]
	v_mfma_f32_16x16x32_bf16 v[110:113], v[114:117], v[218:221], v[110:113]
	v_mfma_f32_16x16x32_bf16 v[94:97], v[114:117], v[226:229], v[94:97]
	v_mfma_f32_16x16x32_bf16 v[90:93], v[122:125], v[226:229], v[90:93]
	v_mfma_f32_16x16x32_bf16 v[74:77], v[122:125], v[234:237], v[74:77]
	v_mfma_f32_16x16x32_bf16 v[78:81], v[114:117], v[234:237], v[78:81]
	v_mfma_f32_16x16x32_bf16 v[142:145], v[118:121], v[200:203], v[142:145]
	v_mfma_f32_16x16x32_bf16 v[138:141], v[134:137], v[200:203], v[138:141]
	v_mfma_f32_16x16x32_bf16 v[106:109], v[134:137], v[222:225], v[106:109]
	v_mfma_f32_16x16x32_bf16 v[110:113], v[118:121], v[222:225], v[110:113]
	v_mfma_f32_16x16x32_bf16 v[94:97], v[118:121], v[230:233], v[94:97]
	v_mfma_f32_16x16x32_bf16 v[90:93], v[134:137], v[230:233], v[90:93]
	v_mfma_f32_16x16x32_bf16 v[74:77], v[134:137], v[238:241], v[74:77]
	v_mfma_f32_16x16x32_bf16 v[78:81], v[118:121], v[238:241], v[78:81]
	s_setprio 0
	s_setprio 1
	v_mfma_f32_16x16x32_bf16 v[130:133], v[146:149], v[196:199], v[130:133]
	v_mfma_f32_16x16x32_bf16 v[126:129], v[180:183], v[196:199], v[126:129]
	v_mfma_f32_16x16x32_bf16 v[98:101], v[180:183], v[218:221], v[98:101]
	v_mfma_f32_16x16x32_bf16 v[102:105], v[146:149], v[218:221], v[102:105]
	v_mfma_f32_16x16x32_bf16 v[86:89], v[146:149], v[226:229], v[86:89]
	v_mfma_f32_16x16x32_bf16 v[82:85], v[180:183], v[226:229], v[82:85]
	v_mfma_f32_16x16x32_bf16 v[66:69], v[180:183], v[234:237], v[66:69]
	v_mfma_f32_16x16x32_bf16 v[70:73], v[146:149], v[234:237], v[70:73]
	v_mfma_f32_16x16x32_bf16 v[130:133], v[150:153], v[200:203], v[130:133]
	v_mfma_f32_16x16x32_bf16 v[126:129], v[184:187], v[200:203], v[126:129]
	v_mfma_f32_16x16x32_bf16 v[98:101], v[184:187], v[222:225], v[98:101]
	v_mfma_f32_16x16x32_bf16 v[102:105], v[150:153], v[222:225], v[102:105]
	v_mfma_f32_16x16x32_bf16 v[86:89], v[150:153], v[230:233], v[86:89]
	v_mfma_f32_16x16x32_bf16 v[82:85], v[184:187], v[230:233], v[82:85]
	v_mfma_f32_16x16x32_bf16 v[66:69], v[184:187], v[238:241], v[66:69]
	v_mfma_f32_16x16x32_bf16 v[70:73], v[150:153], v[238:241], v[70:73]
	s_setprio 0
	s_barrier
; #define PG8_STAGE(bufoff, gbase, voff) do { _Pragma("unroll") for (int _i = 0; _i < 2; ++_i) \
;         __builtin_amdgcn_global_load_lds((const unsigned*)((const char*)(gbase) + (voff)[_i]), (PG8_LAS unsigned*)(lds + (bufoff) + ldsw + _i * 8192), 16, 0, 0); } while (0)
; #define PG8_LDA(dst, b, h) do { _Pragma("unroll") for (int m = 0; m < 4; ++m) _Pragma("unroll") for (int k = 0; k < 2; ++k) dst[m][k] = *(const PG8_LAS bf16x8*)(lds + PG8_SA(b, h) + aoff + m * 2048 + k * 1024); } while (0)
; #define PG8_MMA(ai, bj, At, Bt) do { __builtin_amdgcn_s_setprio(1); _Pragma("unroll") for (int m = 0; m < 4; ++m) _Pragma("unroll") for (int n = 0; n < 2; ++n) _Pragma("unroll") for (int k = 0; k < 2; ++k) \
;         acc[ai][bj][m][n] = __builtin_amdgcn_mfma_f32_16x16x32_bf16(Bt[n][k], At[m][k], acc[ai][bj][m][n], 0, 0, 0); __builtin_amdgcn_s_setprio(0); } while (0)
; #define PG8_WAIT_V(n) asm volatile("s_waitcnt vmcnt(" #n ")" ::: "memory")
; #define PG8_WAIT_L(n) asm volatile("s_waitcnt lgkmcnt(" #n ")" ::: "memory")
; #define PG8_BAR __builtin_amdgcn_s_barrier()
; #define PG8_SCHED __builtin_amdgcn_sched_barrier(0)
; template <class Epi, class Sched, bool ALIGN_EPI = false, bool SP2 = false>
; __device__ __forceinline__ void gemm_phase(PG8_LAS unsigned char* lds, const Gemm g, const Sched& S, const Epi& E) {
;     ...
;             PG8_LDA(At, 1, 1); PG8_STAGE(PG8_SB(1, 0), b3, voffB); PG8_STAGE(PG8_SB(1, 1), b3 + hstep, voffB); PG8_STAGE(PG8_SA(1, 0), a3, voffA);
;             PG8_WAIT_V(8); PG8_WAIT_L(0); PG8_BAR; PG8_MMA(1, 0, At, B0); PG8_MMA(1, 1, At, B1); PG8_BAR; PG8_SCHED;
	s_add_i32 s28, s54, s2
	v_lshl_add_u64 v[166:167], v[166:167], 0, s[34:35]
	s_mov_b32 m0, s28
	ds_read_b128 v[196:199], v194 offset:49152
	ds_read_b128 v[200:203], v194 offset:50176
	ds_read_b128 v[218:221], v194 offset:51200
	ds_read_b128 v[222:225], v194 offset:52224
	ds_read_b128 v[226:229], v194 offset:53248
	ds_read_b128 v[230:233], v194 offset:54272
	ds_read_b128 v[234:237], v194 offset:55296
	ds_read_b128 v[238:241], v194 offset:56320
	global_load_lds_dwordx4 v[166:167], off
	s_add_i32 m0, s28, 0x2000
	s_add_u32 s26, s26, 0x80080
	v_lshl_add_u64 v[166:167], v[188:189], 0, s[34:35]
	s_addc_u32 s27, s27, 0
	s_add_i32 s28, s55, s2
	global_load_lds_dwordx4 v[166:167], off
	v_lshl_add_u64 v[166:167], s[26:27], 0, v[0:1]
	s_mov_b32 m0, s28
	s_nop 0
	global_load_lds_dwordx4 v[166:167], off
	v_lshl_add_u64 v[166:167], s[26:27], 0, v[154:155]
	s_add_i32 m0, s28, 0x2000
	s_nop 0
	global_load_lds_dwordx4 v[166:167], off
	v_lshl_add_u64 v[166:167], v[242:243], 0, s[34:35]
	s_mov_b32 m0, s53
	s_nop 0
	global_load_lds_dwordx4 v[166:167], off
	v_lshl_add_u64 v[166:167], v[244:245], 0, s[34:35]
	s_mov_b32 m0, s73
	s_nop 0
	global_load_lds_dwordx4 v[166:167], off
	s_waitcnt vmcnt(8)
	s_waitcnt lgkmcnt(0)
	s_barrier
	s_setprio 1
	s_waitcnt lgkmcnt(0)
	v_mfma_f32_16x16x32_bf16 v[62:65], v[114:117], v[196:199], v[62:65]
	v_mfma_f32_16x16x32_bf16 v[58:61], v[122:125], v[196:199], v[58:61]
	v_mfma_f32_16x16x32_bf16 v[42:45], v[122:125], v[218:221], v[42:45]
	v_mfma_f32_16x16x32_bf16 v[46:49], v[114:117], v[218:221], v[46:49]
	v_mfma_f32_16x16x32_bf16 v[30:33], v[114:117], v[226:229], v[30:33]
	v_mfma_f32_16x16x32_bf16 v[26:29], v[122:125], v[226:229], v[26:29]
	v_mfma_f32_16x16x32_bf16 v[10:13], v[122:125], v[234:237], v[10:13]
	v_mfma_f32_16x16x32_bf16 v[14:17], v[114:117], v[234:237], v[14:17]
	v_mfma_f32_16x16x32_bf16 v[62:65], v[118:121], v[200:203], v[62:65]
	v_mfma_f32_16x16x32_bf16 v[58:61], v[134:137], v[200:203], v[58:61]
	v_mfma_f32_16x16x32_bf16 v[42:45], v[134:137], v[222:225], v[42:45]
	v_mfma_f32_16x16x32_bf16 v[46:49], v[118:121], v[222:225], v[46:49]
	v_mfma_f32_16x16x32_bf16 v[30:33], v[118:121], v[230:233], v[30:33]
	v_mfma_f32_16x16x32_bf16 v[26:29], v[134:137], v[230:233], v[26:29]
	v_mfma_f32_16x16x32_bf16 v[10:13], v[134:137], v[238:241], v[10:13]
	v_mfma_f32_16x16x32_bf16 v[14:17], v[118:121], v[238:241], v[14:17]
	s_setprio 0
	s_setprio 1
	v_mfma_f32_16x16x32_bf16 v[54:57], v[146:149], v[196:199], v[54:57]
	v_mfma_f32_16x16x32_bf16 v[50:53], v[180:183], v[196:199], v[50:53]
	v_mfma_f32_16x16x32_bf16 v[34:37], v[180:183], v[218:221], v[34:37]
	v_mfma_f32_16x16x32_bf16 v[38:41], v[146:149], v[218:221], v[38:41]
	v_mfma_f32_16x16x32_bf16 v[22:25], v[146:149], v[226:229], v[22:25]
	v_mfma_f32_16x16x32_bf16 v[18:21], v[180:183], v[226:229], v[18:21]
	v_mfma_f32_16x16x32_bf16 v[2:5], v[180:183], v[234:237], v[2:5]
	v_mfma_f32_16x16x32_bf16 v[6:9], v[146:149], v[234:237], v[6:9]
	v_mfma_f32_16x16x32_bf16 v[54:57], v[150:153], v[200:203], v[54:57]
	v_mfma_f32_16x16x32_bf16 v[50:53], v[184:187], v[200:203], v[50:53]
	v_mfma_f32_16x16x32_bf16 v[34:37], v[184:187], v[222:225], v[34:37]
	v_mfma_f32_16x16x32_bf16 v[38:41], v[150:153], v[222:225], v[38:41]
	v_mfma_f32_16x16x32_bf16 v[22:25], v[150:153], v[230:233], v[22:25]
	v_mfma_f32_16x16x32_bf16 v[18:21], v[184:187], v[230:233], v[18:21]
	v_mfma_f32_16x16x32_bf16 v[2:5], v[184:187], v[238:241], v[2:5]
	v_mfma_f32_16x16x32_bf16 v[6:9], v[150:153], v[238:241], v[6:9]
	s_setprio 0
	s_barrier
	s_add_i32 vcc_hi, vcc_hi, 2
	s_add_u32 s16, s16, 0x100
	s_addc_u32 s17, s17, 0
	s_add_u32 s78, s78, 0x100
	s_addc_u32 vcc_lo, vcc_lo, 0
	s_cmp_gt_u32 vcc_hi, 29
	s_cbranch_scc0 .LBB0_553
	s_and_b64 vcc, exec, s[6:7]
	s_cbranch_vccz .LBB0_556
	s_barrier

; #define PG8_STAGE(bufoff, gbase, voff) do { _Pragma("unroll") for (int _i = 0; _i < 2; ++_i) \
;         __builtin_amdgcn_global_load_lds((const unsigned*)((const char*)(gbase) + (voff)[_i]), (PG8_LAS unsigned*)(lds + (bufoff) + ldsw + _i * 8192), 16, 0, 0); } while (0)
; #define PG8_LDA(dst, b, h) do { _Pragma("unroll") for (int m = 0; m < 4; ++m) _Pragma("unroll") for (int k = 0; k < 2; ++k) dst[m][k] = *(const PG8_LAS bf16x8*)(lds + PG8_SA(b, h) + aoff + m * 2048 + k * 1024); } while (0)
; #define PG8_LDB(dst, b, h) do { _Pragma("unroll") for (int n = 0; n < 2; ++n) _Pragma("unroll") for (int k = 0; k < 2; ++k) dst[n][k] = *(const PG8_LAS bf16x8*)(lds + PG8_SB(b, h) + boff + n * 2048 + k * 1024); } while (0)
; #define PG8_MMA(ai, bj, At, Bt) do { __builtin_amdgcn_s_setprio(1); _Pragma("unroll") for (int m = 0; m < 4; ++m) _Pragma("unroll") for (int n = 0; n < 2; ++n) _Pragma("unroll") for (int k = 0; k < 2; ++k) \
;         acc[ai][bj][m][n] = __builtin_amdgcn_mfma_f32_16x16x32_bf16(Bt[n][k], At[m][k], acc[ai][bj][m][n], 0, 0, 0); __builtin_amdgcn_s_setprio(0); } while (0)
; #define PG8_WAIT_V(n) asm volatile("s_waitcnt vmcnt(" #n ")" ::: "memory")
; #define PG8_BAR __builtin_amdgcn_s_barrier()
; template <class Epi, class Sched, bool ALIGN_EPI = false, bool SP2 = false>
; __device__ __forceinline__ void gemm_phase(PG8_LAS unsigned char* lds, const Gemm g, const Sched& S, const Epi& E) {
;     ...
;         for (int t = 0; t < nt; t += 2) {
;             const bool last = (t == nt - 2);
;             const char* a1 = cA + (size_t)(t + 1) * kstep;
;             const char* a2 = last ? nA : cA + (size_t)(t + 2) * kstep; const char* b2 = last ? nB : cB + (size_t)(t + 2) * kstep;
;             const char* a3 = a2 + kstep; const char* b3 = b2 + kstep;
;             if (last && has_next) S.a_ready(nxt);
;             if constexpr (SP2) {
;             PG8_LDB(B0, 0, 0); PG8_LDB(B1, 0, 1); PG8_SCHED; PG8_LDA(At, 0, 0); PG8_STAGE(PG8_SA(1, 1), a1 + hstep, voffA);
;             PG8_WAIT_V(8); PG8_WAIT_L(0); PG8_BAR; PG8_MMA(0, 0, At, B0); PG8_MMA(0, 1, At, B1); PG8_BAR; PG8_SCHED;
;             PG8_LDA(At, 0, 1); PG8_STAGE(PG8_SB(0, 0), b2, voffB); PG8_STAGE(PG8_SB(0, 1), b2 + hstep, voffB); PG8_STAGE(PG8_SA(0, 0), a2, voffA);
;             PG8_WAIT_V(8); PG8_WAIT_L(0); PG8_BAR; PG8_MMA(1, 0, At, B0); PG8_MMA(1, 1, At, B1); PG8_BAR; PG8_SCHED;
.LBB0_659:
	s_add_u32 s26, s16, 0xfff80080
	s_addc_u32 s27, s17, -1
	s_add_i32 s54, 0, 0x10000
	s_cmp_eq_u32 s77, 28
	s_cselect_b32 s29, s23, s27
	s_cselect_b32 s28, s43, s26
	s_cselect_b32 s27, s21, s73
	s_cselect_b32 s26, s52, s53
	s_add_i32 s78, 0, 0x14000
	v_add_u32_e32 v154, s54, v159
	v_add_u32_e32 v163, s78, v159
	ds_read_b128 v[142:145], v154
	ds_read_b128 v[146:149], v154 offset:1024
	ds_read_b128 v[150:153], v154 offset:2048
	ds_read_b128 v[154:157], v154 offset:3072
	ds_read_b128 v[164:167], v163
	ds_read_b128 v[180:183], v163 offset:1024
	ds_read_b128 v[184:187], v163 offset:2048
	ds_read_b128 v[188:191], v163 offset:3072
	v_lshl_add_u64 v[238:239], s[16:17], 0, v[138:139]
	s_add_i32 m0, s45, 0xc000
	ds_read_b128 v[192:195], v162
	ds_read_b128 v[196:199], v162 offset:1024
	ds_read_b128 v[200:203], v162 offset:2048
	ds_read_b128 v[218:221], v162 offset:3072
	ds_read_b128 v[222:225], v162 offset:4096
	ds_read_b128 v[226:229], v162 offset:5120
	ds_read_b128 v[230:233], v162 offset:6144
	ds_read_b128 v[234:237], v162 offset:7168
	global_load_lds_dwordx4 v[238:239], off
	v_lshl_add_u64 v[238:239], s[16:17], 0, v[140:141]
	s_add_i32 m0, s45, 0xe000
	s_nop 0
	global_load_lds_dwordx4 v[238:239], off
	s_waitcnt vmcnt(8)
	s_waitcnt lgkmcnt(0)
	s_barrier
	s_setprio 1
	s_waitcnt lgkmcnt(0)
	v_mfma_f32_16x16x32_bf16 v[126:129], v[142:145], v[192:195], v[126:129]
	v_mfma_f32_16x16x32_bf16 v[118:121], v[150:153], v[192:195], v[118:121]
	v_mfma_f32_16x16x32_bf16 v[102:105], v[150:153], v[200:203], v[102:105]
	v_mfma_f32_16x16x32_bf16 v[110:113], v[142:145], v[200:203], v[110:113]
	v_mfma_f32_16x16x32_bf16 v[94:97], v[142:145], v[222:225], v[94:97]
	v_mfma_f32_16x16x32_bf16 v[86:89], v[150:153], v[222:225], v[86:89]
	v_mfma_f32_16x16x32_bf16 v[70:73], v[150:153], v[230:233], v[70:73]
	v_mfma_f32_16x16x32_bf16 v[78:81], v[142:145], v[230:233], v[78:81]
	v_mfma_f32_16x16x32_bf16 v[126:129], v[146:149], v[196:199], v[126:129]
	v_mfma_f32_16x16x32_bf16 v[118:121], v[154:157], v[196:199], v[118:121]
	v_mfma_f32_16x16x32_bf16 v[102:105], v[154:157], v[218:221], v[102:105]
	v_mfma_f32_16x16x32_bf16 v[110:113], v[146:149], v[218:221], v[110:113]
	v_mfma_f32_16x16x32_bf16 v[94:97], v[146:149], v[226:229], v[94:97]
	v_mfma_f32_16x16x32_bf16 v[86:89], v[154:157], v[226:229], v[86:89]
	v_mfma_f32_16x16x32_bf16 v[70:73], v[154:157], v[234:237], v[70:73]
	v_mfma_f32_16x16x32_bf16 v[78:81], v[146:149], v[234:237], v[78:81]
	s_setprio 0
	s_setprio 1
	v_mfma_f32_16x16x32_bf16 v[122:125], v[164:167], v[192:195], v[122:125]
	v_mfma_f32_16x16x32_bf16 v[114:117], v[184:187], v[192:195], v[114:117]
	v_mfma_f32_16x16x32_bf16 v[98:101], v[184:187], v[200:203], v[98:101]
	v_mfma_f32_16x16x32_bf16 v[106:109], v[164:167], v[200:203], v[106:109]
	v_mfma_f32_16x16x32_bf16 v[90:93], v[164:167], v[222:225], v[90:93]
	v_mfma_f32_16x16x32_bf16 v[82:85], v[184:187], v[222:225], v[82:85]
	v_mfma_f32_16x16x32_bf16 v[66:69], v[184:187], v[230:233], v[66:69]
	v_mfma_f32_16x16x32_bf16 v[74:77], v[164:167], v[230:233], v[74:77]
	v_mfma_f32_16x16x32_bf16 v[122:125], v[180:183], v[196:199], v[122:125]
	v_mfma_f32_16x16x32_bf16 v[114:117], v[188:191], v[196:199], v[114:117]
	v_mfma_f32_16x16x32_bf16 v[98:101], v[188:191], v[218:221], v[98:101]
	v_mfma_f32_16x16x32_bf16 v[106:109], v[180:183], v[218:221], v[106:109]
	v_mfma_f32_16x16x32_bf16 v[90:93], v[180:183], v[226:229], v[90:93]
	v_mfma_f32_16x16x32_bf16 v[82:85], v[188:191], v[226:229], v[82:85]
	v_mfma_f32_16x16x32_bf16 v[66:69], v[188:191], v[234:237], v[66:69]
	v_mfma_f32_16x16x32_bf16 v[74:77], v[180:183], v[234:237], v[74:77]
	s_setprio 0
	s_barrier
	s_add_i32 s54, s54, s38
	v_lshl_add_u64 v[238:239], s[26:27], 0, v[0:1]
	s_mov_b32 m0, s54
	ds_read_b128 v[192:195], v162 offset:16384
	ds_read_b128 v[196:199], v162 offset:17408
	ds_read_b128 v[200:203], v162 offset:18432
	ds_read_b128 v[218:221], v162 offset:19456
	ds_read_b128 v[222:225], v162 offset:20480
	ds_read_b128 v[226:229], v162 offset:21504
	ds_read_b128 v[230:233], v162 offset:22528
	ds_read_b128 v[234:237], v162 offset:23552
	global_load_lds_dwordx4 v[238:239], off
	s_add_i32 m0, s54, 0x2000
	s_add_u32 s54, s26, 0x80000
	v_lshl_add_u64 v[240:241], s[26:27], 0, v[130:131]
	s_addc_u32 s55, s27, 0
	s_add_i32 s78, s78, s38
	global_load_lds_dwordx4 v[240:241], off
	v_lshl_add_u64 v[242:243], s[54:55], 0, v[0:1]
	s_mov_b32 m0, s78
	v_lshl_add_u64 v[244:245], s[28:29], 0, v[132:133]
	global_load_lds_dwordx4 v[242:243], off
	v_lshl_add_u64 v[242:243], s[54:55], 0, v[130:131]
	s_add_i32 m0, s78, 0x2000
	s_nop 0
	global_load_lds_dwordx4 v[242:243], off
	v_lshl_add_u64 v[242:243], s[28:29], 0, v[134:135]
	s_mov_b32 m0, s45
	s_nop 0
	global_load_lds_dwordx4 v[242:243], off
	s_mov_b32 m0, s46
	s_nop 0
	global_load_lds_dwordx4 v[244:245], off
	s_waitcnt vmcnt(8)
	s_waitcnt lgkmcnt(0)
	s_barrier
; #define PG8_STAGE(bufoff, gbase, voff) do { _Pragma("unroll") for (int _i = 0; _i < 2; ++_i) \
;         __builtin_amdgcn_global_load_lds((const unsigned*)((const char*)(gbase) + (voff)[_i]), (PG8_LAS unsigned*)(lds + (bufoff) + ldsw + _i * 8192), 16, 0, 0); } while (0)
; #define PG8_LDA(dst, b, h) do { _Pragma("unroll") for (int m = 0; m < 4; ++m) _Pragma("unroll") for (int k = 0; k < 2; ++k) dst[m][k] = *(const PG8_LAS bf16x8*)(lds + PG8_SA(b, h) + aoff + m * 2048 + k * 1024); } while (0)
; #define PG8_LDB(dst, b, h) do { _Pragma("unroll") for (int n = 0; n < 2; ++n) _Pragma("unroll") for (int k = 0; k < 2; ++k) dst[n][k] = *(const PG8_LAS bf16x8*)(lds + PG8_SB(b, h) + boff + n * 2048 + k * 1024); } while (0)
; #define PG8_MMA(ai, bj, At, Bt) do { __builtin_amdgcn_s_setprio(1); _Pragma("unroll") for (int m = 0; m < 4; ++m) _Pragma("unroll") for (int n = 0; n < 2; ++n) _Pragma("unroll") for (int k = 0; k < 2; ++k) \
;         acc[ai][bj][m][n] = __builtin_amdgcn_mfma_f32_16x16x32_bf16(Bt[n][k], At[m][k], acc[ai][bj][m][n], 0, 0, 0); __builtin_amdgcn_s_setprio(0); } while (0)
; #define PG8_WAIT_V(n) asm volatile("s_waitcnt vmcnt(" #n ")" ::: "memory")
; #define PG8_WAIT_L(n) asm volatile("s_waitcnt lgkmcnt(" #n ")" ::: "memory")
; #define PG8_BAR __builtin_amdgcn_s_barrier()
; #define PG8_SCHED __builtin_amdgcn_sched_barrier(0)
; template <class Epi, class Sched, bool ALIGN_EPI = false, bool SP2 = false>
; __device__ __forceinline__ void gemm_phase(PG8_LAS unsigned char* lds, const Gemm g, const Sched& S, const Epi& E) {
;     ...
;             PG8_WAIT_V(8); PG8_WAIT_L(0); PG8_BAR; PG8_MMA(1, 0, At, B0); PG8_MMA(1, 1, At, B1); PG8_BAR; PG8_SCHED;
;             PG8_LDB(B0, 1, 0); PG8_LDB(B1, 1, 1); PG8_SCHED; PG8_LDA(At, 1, 0); PG8_STAGE(PG8_SA(0, 1), a2 + hstep, voffA);
;             PG8_WAIT_V(8); PG8_WAIT_L(0); PG8_BAR; PG8_MMA(0, 0, At, B0); PG8_MMA(0, 1, At, B1); PG8_BAR; PG8_SCHED;
;             PG8_LDA(At, 1, 1); PG8_STAGE(PG8_SB(1, 0), b3, voffB); PG8_STAGE(PG8_SB(1, 1), b3 + hstep, voffB); PG8_STAGE(PG8_SA(1, 0), a3, voffA);
	s_setprio 1
	s_waitcnt lgkmcnt(0)
	v_mfma_f32_16x16x32_bf16 v[62:65], v[142:145], v[192:195], v[62:65]
	v_mfma_f32_16x16x32_bf16 v[54:57], v[150:153], v[192:195], v[54:57]
	v_mfma_f32_16x16x32_bf16 v[38:41], v[150:153], v[200:203], v[38:41]
	v_mfma_f32_16x16x32_bf16 v[46:49], v[142:145], v[200:203], v[46:49]
	v_mfma_f32_16x16x32_bf16 v[30:33], v[142:145], v[222:225], v[30:33]
	v_mfma_f32_16x16x32_bf16 v[22:25], v[150:153], v[222:225], v[22:25]
	v_mfma_f32_16x16x32_bf16 v[6:9], v[150:153], v[230:233], v[6:9]
	v_mfma_f32_16x16x32_bf16 v[14:17], v[142:145], v[230:233], v[14:17]
	v_mfma_f32_16x16x32_bf16 v[62:65], v[146:149], v[196:199], v[62:65]
	v_mfma_f32_16x16x32_bf16 v[54:57], v[154:157], v[196:199], v[54:57]
	v_mfma_f32_16x16x32_bf16 v[38:41], v[154:157], v[218:221], v[38:41]
	v_mfma_f32_16x16x32_bf16 v[46:49], v[146:149], v[218:221], v[46:49]
	v_mfma_f32_16x16x32_bf16 v[30:33], v[146:149], v[226:229], v[30:33]
	v_mfma_f32_16x16x32_bf16 v[22:25], v[154:157], v[226:229], v[22:25]
	v_mfma_f32_16x16x32_bf16 v[6:9], v[154:157], v[234:237], v[6:9]
	v_mfma_f32_16x16x32_bf16 v[14:17], v[146:149], v[234:237], v[14:17]
	s_setprio 0
	s_setprio 1
	v_mfma_f32_16x16x32_bf16 v[58:61], v[164:167], v[192:195], v[58:61]
	v_mfma_f32_16x16x32_bf16 v[50:53], v[184:187], v[192:195], v[50:53]
	v_mfma_f32_16x16x32_bf16 v[34:37], v[184:187], v[200:203], v[34:37]
	v_mfma_f32_16x16x32_bf16 v[42:45], v[164:167], v[200:203], v[42:45]
	v_mfma_f32_16x16x32_bf16 v[26:29], v[164:167], v[222:225], v[26:29]
	v_mfma_f32_16x16x32_bf16 v[18:21], v[184:187], v[222:225], v[18:21]
	v_mfma_f32_16x16x32_bf16 v[2:5], v[184:187], v[230:233], v[2:5]
	v_mfma_f32_16x16x32_bf16 v[10:13], v[164:167], v[230:233], v[10:13]
	v_mfma_f32_16x16x32_bf16 v[58:61], v[180:183], v[196:199], v[58:61]
	v_mfma_f32_16x16x32_bf16 v[50:53], v[188:191], v[196:199], v[50:53]
	v_mfma_f32_16x16x32_bf16 v[34:37], v[188:191], v[218:221], v[34:37]
	v_mfma_f32_16x16x32_bf16 v[42:45], v[180:183], v[218:221], v[42:45]
	v_mfma_f32_16x16x32_bf16 v[26:29], v[180:183], v[226:229], v[26:29]
	v_mfma_f32_16x16x32_bf16 v[18:21], v[188:191], v[226:229], v[18:21]
	v_mfma_f32_16x16x32_bf16 v[2:5], v[188:191], v[234:237], v[2:5]
	v_mfma_f32_16x16x32_bf16 v[10:13], v[180:183], v[234:237], v[10:13]
	s_setprio 0
	s_barrier
	s_add_i32 s54, 0, 0x18000
	s_add_i32 s55, 0, 0x1c000
	v_add_u32_e32 v154, s54, v159
	v_add_u32_e32 v163, s55, v159
	ds_read_b128 v[142:145], v154
	ds_read_b128 v[146:149], v154 offset:1024
	ds_read_b128 v[150:153], v154 offset:2048
	ds_read_b128 v[154:157], v154 offset:3072
	ds_read_b128 v[164:167], v163
	ds_read_b128 v[180:183], v163 offset:1024
	ds_read_b128 v[184:187], v163 offset:2048
	ds_read_b128 v[188:191], v163 offset:3072
	s_add_u32 s28, s28, 0x80000
	s_addc_u32 s29, s29, 0
	s_mov_b32 m0, s47
	v_lshl_add_u64 v[246:247], s[28:29], 0, v[134:135]
	ds_read_b128 v[192:195], v162 offset:32768
	ds_read_b128 v[196:199], v162 offset:33792
	ds_read_b128 v[200:203], v162 offset:34816
	ds_read_b128 v[218:221], v162 offset:35840
	ds_read_b128 v[222:225], v162 offset:36864
	ds_read_b128 v[226:229], v162 offset:37888
	ds_read_b128 v[230:233], v162 offset:38912
	ds_read_b128 v[234:237], v162 offset:39936
	global_load_lds_dwordx4 v[246:247], off
	v_lshl_add_u64 v[246:247], s[28:29], 0, v[132:133]
	s_mov_b32 m0, s48
	s_nop 0
	global_load_lds_dwordx4 v[246:247], off
	s_waitcnt vmcnt(8)
	s_waitcnt lgkmcnt(0)
	s_barrier
	s_setprio 1
	s_waitcnt lgkmcnt(0)
	v_mfma_f32_16x16x32_bf16 v[126:129], v[142:145], v[192:195], v[126:129]
	v_mfma_f32_16x16x32_bf16 v[118:121], v[150:153], v[192:195], v[118:121]
	v_mfma_f32_16x16x32_bf16 v[102:105], v[150:153], v[200:203], v[102:105]
	v_mfma_f32_16x16x32_bf16 v[110:113], v[142:145], v[200:203], v[110:113]
	v_mfma_f32_16x16x32_bf16 v[94:97], v[142:145], v[222:225], v[94:97]
	v_mfma_f32_16x16x32_bf16 v[86:89], v[150:153], v[222:225], v[86:89]
	v_mfma_f32_16x16x32_bf16 v[70:73], v[150:153], v[230:233], v[70:73]
	v_mfma_f32_16x16x32_bf16 v[78:81], v[142:145], v[230:233], v[78:81]
	v_mfma_f32_16x16x32_bf16 v[126:129], v[146:149], v[196:199], v[126:129]
	v_mfma_f32_16x16x32_bf16 v[118:121], v[154:157], v[196:199], v[118:121]
	v_mfma_f32_16x16x32_bf16 v[102:105], v[154:157], v[218:221], v[102:105]
	v_mfma_f32_16x16x32_bf16 v[110:113], v[146:149], v[218:221], v[110:113]
	v_mfma_f32_16x16x32_bf16 v[94:97], v[146:149], v[226:229], v[94:97]
	v_mfma_f32_16x16x32_bf16 v[86:89], v[154:157], v[226:229], v[86:89]
	v_mfma_f32_16x16x32_bf16 v[70:73], v[154:157], v[234:237], v[70:73]
	v_mfma_f32_16x16x32_bf16 v[78:81], v[146:149], v[234:237], v[78:81]
	s_setprio 0
	s_setprio 1
	v_mfma_f32_16x16x32_bf16 v[122:125], v[164:167], v[192:195], v[122:125]
	v_mfma_f32_16x16x32_bf16 v[114:117], v[184:187], v[192:195], v[114:117]
	v_mfma_f32_16x16x32_bf16 v[98:101], v[184:187], v[200:203], v[98:101]
	v_mfma_f32_16x16x32_bf16 v[106:109], v[164:167], v[200:203], v[106:109]
	v_mfma_f32_16x16x32_bf16 v[90:93], v[164:167], v[222:225], v[90:93]
	v_mfma_f32_16x16x32_bf16 v[82:85], v[184:187], v[222:225], v[82:85]
	v_mfma_f32_16x16x32_bf16 v[66:69], v[184:187], v[230:233], v[66:69]
	v_mfma_f32_16x16x32_bf16 v[74:77], v[164:167], v[230:233], v[74:77]
	v_mfma_f32_16x16x32_bf16 v[122:125], v[180:183], v[196:199], v[122:125]
	v_mfma_f32_16x16x32_bf16 v[114:117], v[188:191], v[196:199], v[114:117]
	v_mfma_f32_16x16x32_bf16 v[98:101], v[188:191], v[218:221], v[98:101]
	v_mfma_f32_16x16x32_bf16 v[106:109], v[180:183], v[218:221], v[106:109]
	v_mfma_f32_16x16x32_bf16 v[90:93], v[180:183], v[226:229], v[90:93]
	v_mfma_f32_16x16x32_bf16 v[82:85], v[188:191], v[226:229], v[82:85]
	v_mfma_f32_16x16x32_bf16 v[66:69], v[188:191], v[234:237], v[66:69]
	v_mfma_f32_16x16x32_bf16 v[74:77], v[180:183], v[234:237], v[74:77]
	s_setprio 0
	s_barrier
; #define PG8_STAGE(bufoff, gbase, voff) do { _Pragma("unroll") for (int _i = 0; _i < 2; ++_i) \
;         __builtin_amdgcn_global_load_lds((const unsigned*)((const char*)(gbase) + (voff)[_i]), (PG8_LAS unsigned*)(lds + (bufoff) + ldsw + _i * 8192), 16, 0, 0); } while (0)
; #define PG8_LDA(dst, b, h) do { _Pragma("unroll") for (int m = 0; m < 4; ++m) _Pragma("unroll") for (int k = 0; k < 2; ++k) dst[m][k] = *(const PG8_LAS bf16x8*)(lds + PG8_SA(b, h) + aoff + m * 2048 + k * 1024); } while (0)
; #define PG8_MMA(ai, bj, At, Bt) do { __builtin_amdgcn_s_setprio(1); _Pragma("unroll") for (int m = 0; m < 4; ++m) _Pragma("unroll") for (int n = 0; n < 2; ++n) _Pragma("unroll") for (int k = 0; k < 2; ++k) \
;         acc[ai][bj][m][n] = __builtin_amdgcn_mfma_f32_16x16x32_bf16(Bt[n][k], At[m][k], acc[ai][bj][m][n], 0, 0, 0); __builtin_amdgcn_s_setprio(0); } while (0)
; #define PG8_WAIT_V(n) asm volatile("s_waitcnt vmcnt(" #n ")" ::: "memory")
; #define PG8_WAIT_L(n) asm volatile("s_waitcnt lgkmcnt(" #n ")" ::: "memory")
; #define PG8_BAR __builtin_amdgcn_s_barrier()
; #define PG8_SCHED __builtin_amdgcn_sched_barrier(0)
; template <class Epi, class Sched, bool ALIGN_EPI = false, bool SP2 = false>
; __device__ __forceinline__ void gemm_phase(PG8_LAS unsigned char* lds, const Gemm g, const Sched& S, const Epi& E) {
;     ...
;             PG8_LDA(At, 1, 1); PG8_STAGE(PG8_SB(1, 0), b3, voffB); PG8_STAGE(PG8_SB(1, 1), b3 + hstep, voffB); PG8_STAGE(PG8_SA(1, 0), a3, voffA);
;             PG8_WAIT_V(8); PG8_WAIT_L(0); PG8_BAR; PG8_MMA(1, 0, At, B0); PG8_MMA(1, 1, At, B1); PG8_BAR; PG8_SCHED;
	s_add_i32 s28, s54, s38
	v_lshl_add_u64 v[238:239], v[238:239], 0, s[34:35]
	s_mov_b32 m0, s28
	ds_read_b128 v[192:195], v162 offset:49152
	ds_read_b128 v[196:199], v162 offset:50176
	ds_read_b128 v[200:203], v162 offset:51200
	ds_read_b128 v[218:221], v162 offset:52224
	ds_read_b128 v[222:225], v162 offset:53248
	ds_read_b128 v[226:229], v162 offset:54272
	ds_read_b128 v[230:233], v162 offset:55296
	ds_read_b128 v[234:237], v162 offset:56320
	global_load_lds_dwordx4 v[238:239], off
	s_add_i32 m0, s28, 0x2000
	s_add_u32 s26, s26, 0x80080
	v_lshl_add_u64 v[238:239], v[240:241], 0, s[34:35]
	s_addc_u32 s27, s27, 0
	s_add_i32 s28, s55, s38
	global_load_lds_dwordx4 v[238:239], off
	v_lshl_add_u64 v[238:239], s[26:27], 0, v[0:1]
	s_mov_b32 m0, s28
	s_nop 0
	global_load_lds_dwordx4 v[238:239], off
	v_lshl_add_u64 v[238:239], s[26:27], 0, v[130:131]
	s_add_i32 m0, s28, 0x2000
	s_nop 0
	global_load_lds_dwordx4 v[238:239], off
	v_lshl_add_u64 v[238:239], v[242:243], 0, s[34:35]
	s_mov_b32 m0, s4
	s_nop 0
	global_load_lds_dwordx4 v[238:239], off
	v_lshl_add_u64 v[238:239], v[244:245], 0, s[34:35]
	s_mov_b32 m0, s49
	s_nop 0
	global_load_lds_dwordx4 v[238:239], off
	s_waitcnt vmcnt(8)
	s_waitcnt lgkmcnt(0)
	s_barrier
	s_setprio 1
	s_waitcnt lgkmcnt(0)
	v_mfma_f32_16x16x32_bf16 v[62:65], v[142:145], v[192:195], v[62:65]
	v_mfma_f32_16x16x32_bf16 v[54:57], v[150:153], v[192:195], v[54:57]
	v_mfma_f32_16x16x32_bf16 v[38:41], v[150:153], v[200:203], v[38:41]
	v_mfma_f32_16x16x32_bf16 v[46:49], v[142:145], v[200:203], v[46:49]
	v_mfma_f32_16x16x32_bf16 v[30:33], v[142:145], v[222:225], v[30:33]
	v_mfma_f32_16x16x32_bf16 v[22:25], v[150:153], v[222:225], v[22:25]
	v_mfma_f32_16x16x32_bf16 v[6:9], v[150:153], v[230:233], v[6:9]
	v_mfma_f32_16x16x32_bf16 v[14:17], v[142:145], v[230:233], v[14:17]
	v_mfma_f32_16x16x32_bf16 v[62:65], v[146:149], v[196:199], v[62:65]
	v_mfma_f32_16x16x32_bf16 v[54:57], v[154:157], v[196:199], v[54:57]
	v_mfma_f32_16x16x32_bf16 v[38:41], v[154:157], v[218:221], v[38:41]
	v_mfma_f32_16x16x32_bf16 v[46:49], v[146:149], v[218:221], v[46:49]
	v_mfma_f32_16x16x32_bf16 v[30:33], v[146:149], v[226:229], v[30:33]
	v_mfma_f32_16x16x32_bf16 v[22:25], v[154:157], v[226:229], v[22:25]
	v_mfma_f32_16x16x32_bf16 v[6:9], v[154:157], v[234:237], v[6:9]
	v_mfma_f32_16x16x32_bf16 v[14:17], v[146:149], v[234:237], v[14:17]
	s_setprio 0
	s_setprio 1
	v_mfma_f32_16x16x32_bf16 v[58:61], v[164:167], v[192:195], v[58:61]
	v_mfma_f32_16x16x32_bf16 v[50:53], v[184:187], v[192:195], v[50:53]
	v_mfma_f32_16x16x32_bf16 v[34:37], v[184:187], v[200:203], v[34:37]
	v_mfma_f32_16x16x32_bf16 v[42:45], v[164:167], v[200:203], v[42:45]
	v_mfma_f32_16x16x32_bf16 v[26:29], v[164:167], v[222:225], v[26:29]
	v_mfma_f32_16x16x32_bf16 v[18:21], v[184:187], v[222:225], v[18:21]
	v_mfma_f32_16x16x32_bf16 v[2:5], v[184:187], v[230:233], v[2:5]
	v_mfma_f32_16x16x32_bf16 v[10:13], v[164:167], v[230:233], v[10:13]
	v_mfma_f32_16x16x32_bf16 v[58:61], v[180:183], v[196:199], v[58:61]
	v_mfma_f32_16x16x32_bf16 v[50:53], v[188:191], v[196:199], v[50:53]
	v_mfma_f32_16x16x32_bf16 v[34:37], v[188:191], v[218:221], v[34:37]
	v_mfma_f32_16x16x32_bf16 v[42:45], v[180:183], v[218:221], v[42:45]
	v_mfma_f32_16x16x32_bf16 v[26:29], v[180:183], v[226:229], v[26:29]
	v_mfma_f32_16x16x32_bf16 v[18:21], v[188:191], v[226:229], v[18:21]
	v_mfma_f32_16x16x32_bf16 v[2:5], v[188:191], v[234:237], v[2:5]
	v_mfma_f32_16x16x32_bf16 v[10:13], v[180:183], v[234:237], v[10:13]
	s_setprio 0
	s_barrier
	s_add_i32 s77, s77, 2
	s_add_u32 s16, s16, 0x100
	s_addc_u32 s17, s17, 0
	s_add_u32 s53, s53, 0x100
	s_addc_u32 s73, s73, 0
	s_cmp_gt_u32 s77, 29
	s_cbranch_scc0 .LBB0_659
	s_and_b64 vcc, exec, s[18:19]
	s_cbranch_vccz .LBB0_662
	s_barrier

; #define PG8_STAGE(bufoff, gbase, voff) do { _Pragma("unroll") for (int _i = 0; _i < 2; ++_i) \
;         __builtin_amdgcn_global_load_lds((const unsigned*)((const char*)(gbase) + (voff)[_i]), (PG8_LAS unsigned*)(lds + (bufoff) + ldsw + _i * 8192), 16, 0, 0); } while (0)
; #define PG8_LDA(dst, b, h) do { _Pragma("unroll") for (int m = 0; m < 4; ++m) _Pragma("unroll") for (int k = 0; k < 2; ++k) dst[m][k] = *(const PG8_LAS bf16x8*)(lds + PG8_SA(b, h) + aoff + m * 2048 + k * 1024); } while (0)
; #define PG8_LDB(dst, b, h) do { _Pragma("unroll") for (int n = 0; n < 2; ++n) _Pragma("unroll") for (int k = 0; k < 2; ++k) dst[n][k] = *(const PG8_LAS bf16x8*)(lds + PG8_SB(b, h) + boff + n * 2048 + k * 1024); } while (0)
; #define PG8_MMA(ai, bj, At, Bt) do { __builtin_amdgcn_s_setprio(1); _Pragma("unroll") for (int m = 0; m < 4; ++m) _Pragma("unroll") for (int n = 0; n < 2; ++n) _Pragma("unroll") for (int k = 0; k < 2; ++k) \
;         acc[ai][bj][m][n] = __builtin_amdgcn_mfma_f32_16x16x32_bf16(Bt[n][k], At[m][k], acc[ai][bj][m][n], 0, 0, 0); __builtin_amdgcn_s_setprio(0); } while (0)
; #define PG8_WAIT_V(n) asm volatile("s_waitcnt vmcnt(" #n ")" ::: "memory")
; #define PG8_BAR __builtin_amdgcn_s_barrier()
; template <class Epi, class Sched, bool ALIGN_EPI = false, bool SP2 = false>
; __device__ __forceinline__ void gemm_phase(PG8_LAS unsigned char* lds, const Gemm g, const Sched& S, const Epi& E) {
;     ...
;         for (int t = 0; t < nt; t += 2) {
;             const bool last = (t == nt - 2);
;             const char* a1 = cA + (size_t)(t + 1) * kstep;
;             const char* a2 = last ? nA : cA + (size_t)(t + 2) * kstep; const char* b2 = last ? nB : cB + (size_t)(t + 2) * kstep;
;             const char* a3 = a2 + kstep; const char* b3 = b2 + kstep;
;             if (last && has_next) S.a_ready(nxt);
;             if constexpr (SP2) {
;             PG8_LDB(B0, 0, 0); PG8_LDB(B1, 0, 1); PG8_SCHED; PG8_LDA(At, 0, 0); PG8_STAGE(PG8_SA(1, 1), a1 + hstep, voffA);
;             PG8_WAIT_V(8); PG8_WAIT_L(0); PG8_BAR; PG8_MMA(0, 0, At, B0); PG8_MMA(0, 1, At, B1); PG8_BAR; PG8_SCHED;
;             PG8_LDA(At, 0, 1); PG8_STAGE(PG8_SB(0, 0), b2, voffB); PG8_STAGE(PG8_SB(0, 1), b2 + hstep, voffB); PG8_STAGE(PG8_SA(0, 0), a2, voffA);
;             PG8_WAIT_V(8); PG8_WAIT_L(0); PG8_BAR; PG8_MMA(1, 0, At, B0); PG8_MMA(1, 1, At, B1); PG8_BAR; PG8_SCHED;
.LBB0_802:
	s_add_u32 s24, s22, 0x100
	s_addc_u32 s25, s23, 0
	s_add_i32 s54, 0, 0x10000
	s_cmpk_eq_i32 s78, 0x54
	s_cselect_b32 s29, s19, s25
	s_cselect_b32 s28, s18, s24
	s_cselect_b32 s27, s21, s45
	s_cselect_b32 s26, s20, s44
	s_add_i32 s55, 0, 0x14000
	v_add_u32_e32 v142, s54, v199
	v_add_u32_e32 v182, s55, v199
	ds_read_b128 v[122:125], v142
	ds_read_b128 v[134:137], v142 offset:1024
	ds_read_b128 v[138:141], v142 offset:2048
	ds_read_b128 v[142:145], v142 offset:3072
	ds_read_b128 v[146:149], v182
	ds_read_b128 v[150:153], v182 offset:1024
	ds_read_b128 v[154:157], v182 offset:2048
	ds_read_b128 v[182:185], v182 offset:3072
	v_lshl_add_u64 v[238:239], s[22:23], 0, v[166:167]
	s_add_i32 m0, s46, 0xc000
	ds_read_b128 v[186:189], v202
	ds_read_b128 v[190:193], v202 offset:1024
	ds_read_b128 v[194:197], v202 offset:2048
	ds_read_b128 v[218:221], v202 offset:3072
	ds_read_b128 v[222:225], v202 offset:4096
	ds_read_b128 v[226:229], v202 offset:5120
	ds_read_b128 v[230:233], v202 offset:6144
	ds_read_b128 v[234:237], v202 offset:7168
	global_load_lds_dwordx4 v[238:239], off
	v_lshl_add_u64 v[238:239], s[22:23], 0, v[180:181]
	s_add_i32 m0, s46, 0xe000
	s_nop 0
	global_load_lds_dwordx4 v[238:239], off
	s_waitcnt vmcnt(8)
	s_waitcnt lgkmcnt(0)
	s_barrier
	s_setprio 1
	s_waitcnt lgkmcnt(0)
	v_mfma_f32_16x16x32_bf16 v[130:133], v[122:125], v[186:189], v[130:133]
	v_mfma_f32_16x16x32_bf16 v[126:129], v[138:141], v[186:189], v[126:129]
	v_mfma_f32_16x16x32_bf16 v[106:109], v[138:141], v[194:197], v[106:109]
	v_mfma_f32_16x16x32_bf16 v[110:113], v[122:125], v[194:197], v[110:113]
	v_mfma_f32_16x16x32_bf16 v[94:97], v[122:125], v[222:225], v[94:97]
	v_mfma_f32_16x16x32_bf16 v[90:93], v[138:141], v[222:225], v[90:93]
	v_mfma_f32_16x16x32_bf16 v[74:77], v[138:141], v[230:233], v[74:77]
	v_mfma_f32_16x16x32_bf16 v[78:81], v[122:125], v[230:233], v[78:81]
	v_mfma_f32_16x16x32_bf16 v[130:133], v[134:137], v[190:193], v[130:133]
	v_mfma_f32_16x16x32_bf16 v[126:129], v[142:145], v[190:193], v[126:129]
	v_mfma_f32_16x16x32_bf16 v[106:109], v[142:145], v[218:221], v[106:109]
	v_mfma_f32_16x16x32_bf16 v[110:113], v[134:137], v[218:221], v[110:113]
	v_mfma_f32_16x16x32_bf16 v[94:97], v[134:137], v[226:229], v[94:97]
	v_mfma_f32_16x16x32_bf16 v[90:93], v[142:145], v[226:229], v[90:93]
	v_mfma_f32_16x16x32_bf16 v[74:77], v[142:145], v[234:237], v[74:77]
	v_mfma_f32_16x16x32_bf16 v[78:81], v[134:137], v[234:237], v[78:81]
	s_setprio 0
	s_setprio 1
	v_mfma_f32_16x16x32_bf16 v[118:121], v[146:149], v[186:189], v[118:121]
	v_mfma_f32_16x16x32_bf16 v[114:117], v[154:157], v[186:189], v[114:117]
	v_mfma_f32_16x16x32_bf16 v[98:101], v[154:157], v[194:197], v[98:101]
	v_mfma_f32_16x16x32_bf16 v[102:105], v[146:149], v[194:197], v[102:105]
	v_mfma_f32_16x16x32_bf16 v[86:89], v[146:149], v[222:225], v[86:89]
	v_mfma_f32_16x16x32_bf16 v[82:85], v[154:157], v[222:225], v[82:85]
	v_mfma_f32_16x16x32_bf16 v[66:69], v[154:157], v[230:233], v[66:69]
	v_mfma_f32_16x16x32_bf16 v[70:73], v[146:149], v[230:233], v[70:73]
	v_mfma_f32_16x16x32_bf16 v[118:121], v[150:153], v[190:193], v[118:121]
	v_mfma_f32_16x16x32_bf16 v[114:117], v[182:185], v[190:193], v[114:117]
	v_mfma_f32_16x16x32_bf16 v[98:101], v[182:185], v[218:221], v[98:101]
	v_mfma_f32_16x16x32_bf16 v[102:105], v[150:153], v[218:221], v[102:105]
	v_mfma_f32_16x16x32_bf16 v[86:89], v[150:153], v[226:229], v[86:89]
	v_mfma_f32_16x16x32_bf16 v[82:85], v[182:185], v[226:229], v[82:85]
	v_mfma_f32_16x16x32_bf16 v[66:69], v[182:185], v[234:237], v[66:69]
	v_mfma_f32_16x16x32_bf16 v[70:73], v[150:153], v[234:237], v[70:73]
	s_setprio 0
	s_barrier
	s_add_i32 s22, s54, s2
	v_lshl_add_u64 v[238:239], s[26:27], 0, v[0:1]
	s_mov_b32 m0, s22
	ds_read_b128 v[186:189], v202 offset:16384
	ds_read_b128 v[190:193], v202 offset:17408
	ds_read_b128 v[194:197], v202 offset:18432
	ds_read_b128 v[218:221], v202 offset:19456
	ds_read_b128 v[222:225], v202 offset:20480
	ds_read_b128 v[226:229], v202 offset:21504
	ds_read_b128 v[230:233], v202 offset:22528
	ds_read_b128 v[234:237], v202 offset:23552
	global_load_lds_dwordx4 v[238:239], off
	s_add_i32 m0, s22, 0x2000
	s_add_u32 s22, s26, 0x160000
	v_lshl_add_u64 v[240:241], s[26:27], 0, v[158:159]
	s_addc_u32 s23, s27, 0
	s_add_i32 s54, s55, s2
	global_load_lds_dwordx4 v[240:241], off
	v_lshl_add_u64 v[242:243], s[22:23], 0, v[0:1]
	s_mov_b32 m0, s54
	v_lshl_add_u64 v[244:245], s[28:29], 0, v[160:161]
	global_load_lds_dwordx4 v[242:243], off
	v_lshl_add_u64 v[242:243], s[22:23], 0, v[158:159]
	s_add_i32 m0, s54, 0x2000
	s_nop 0
	global_load_lds_dwordx4 v[242:243], off
	v_lshl_add_u64 v[242:243], s[28:29], 0, v[162:163]
	s_mov_b32 m0, s46
	s_nop 0
	global_load_lds_dwordx4 v[242:243], off
	s_mov_b32 m0, s47
	s_nop 0
	global_load_lds_dwordx4 v[244:245], off
	s_waitcnt vmcnt(8)
	s_waitcnt lgkmcnt(0)
	s_barrier
; #define PG8_STAGE(bufoff, gbase, voff) do { _Pragma("unroll") for (int _i = 0; _i < 2; ++_i) \
;         __builtin_amdgcn_global_load_lds((const unsigned*)((const char*)(gbase) + (voff)[_i]), (PG8_LAS unsigned*)(lds + (bufoff) + ldsw + _i * 8192), 16, 0, 0); } while (0)
; #define PG8_LDA(dst, b, h) do { _Pragma("unroll") for (int m = 0; m < 4; ++m) _Pragma("unroll") for (int k = 0; k < 2; ++k) dst[m][k] = *(const PG8_LAS bf16x8*)(lds + PG8_SA(b, h) + aoff + m * 2048 + k * 1024); } while (0)
; #define PG8_LDB(dst, b, h) do { _Pragma("unroll") for (int n = 0; n < 2; ++n) _Pragma("unroll") for (int k = 0; k < 2; ++k) dst[n][k] = *(const PG8_LAS bf16x8*)(lds + PG8_SB(b, h) + boff + n * 2048 + k * 1024); } while (0)
; #define PG8_MMA(ai, bj, At, Bt) do { __builtin_amdgcn_s_setprio(1); _Pragma("unroll") for (int m = 0; m < 4; ++m) _Pragma("unroll") for (int n = 0; n < 2; ++n) _Pragma("unroll") for (int k = 0; k < 2; ++k) \
;         acc[ai][bj][m][n] = __builtin_amdgcn_mfma_f32_16x16x32_bf16(Bt[n][k], At[m][k], acc[ai][bj][m][n], 0, 0, 0); __builtin_amdgcn_s_setprio(0); } while (0)
; #define PG8_WAIT_V(n) asm volatile("s_waitcnt vmcnt(" #n ")" ::: "memory")
; #define PG8_WAIT_L(n) asm volatile("s_waitcnt lgkmcnt(" #n ")" ::: "memory")
; #define PG8_BAR __builtin_amdgcn_s_barrier()
; #define PG8_SCHED __builtin_amdgcn_sched_barrier(0)
; template <class Epi, class Sched, bool ALIGN_EPI = false, bool SP2 = false>
; __device__ __forceinline__ void gemm_phase(PG8_LAS unsigned char* lds, const Gemm g, const Sched& S, const Epi& E) {
;     ...
;             PG8_WAIT_V(8); PG8_WAIT_L(0); PG8_BAR; PG8_MMA(1, 0, At, B0); PG8_MMA(1, 1, At, B1); PG8_BAR; PG8_SCHED;
;             PG8_LDB(B0, 1, 0); PG8_LDB(B1, 1, 1); PG8_SCHED; PG8_LDA(At, 1, 0); PG8_STAGE(PG8_SA(0, 1), a2 + hstep, voffA);
;             PG8_WAIT_V(8); PG8_WAIT_L(0); PG8_BAR; PG8_MMA(0, 0, At, B0); PG8_MMA(0, 1, At, B1); PG8_BAR; PG8_SCHED;
;             PG8_LDA(At, 1, 1); PG8_STAGE(PG8_SB(1, 0), b3, voffB); PG8_STAGE(PG8_SB(1, 1), b3 + hstep, voffB); PG8_STAGE(PG8_SA(1, 0), a3, voffA);
	s_setprio 1
	s_waitcnt lgkmcnt(0)
	v_mfma_f32_16x16x32_bf16 v[62:65], v[122:125], v[186:189], v[62:65]
	v_mfma_f32_16x16x32_bf16 v[58:61], v[138:141], v[186:189], v[58:61]
	v_mfma_f32_16x16x32_bf16 v[42:45], v[138:141], v[194:197], v[42:45]
	v_mfma_f32_16x16x32_bf16 v[46:49], v[122:125], v[194:197], v[46:49]
	v_mfma_f32_16x16x32_bf16 v[30:33], v[122:125], v[222:225], v[30:33]
	v_mfma_f32_16x16x32_bf16 v[26:29], v[138:141], v[222:225], v[26:29]
	v_mfma_f32_16x16x32_bf16 v[10:13], v[138:141], v[230:233], v[10:13]
	v_mfma_f32_16x16x32_bf16 v[14:17], v[122:125], v[230:233], v[14:17]
	v_mfma_f32_16x16x32_bf16 v[62:65], v[134:137], v[190:193], v[62:65]
	v_mfma_f32_16x16x32_bf16 v[58:61], v[142:145], v[190:193], v[58:61]
	v_mfma_f32_16x16x32_bf16 v[42:45], v[142:145], v[218:221], v[42:45]
	v_mfma_f32_16x16x32_bf16 v[46:49], v[134:137], v[218:221], v[46:49]
	v_mfma_f32_16x16x32_bf16 v[30:33], v[134:137], v[226:229], v[30:33]
	v_mfma_f32_16x16x32_bf16 v[26:29], v[142:145], v[226:229], v[26:29]
	v_mfma_f32_16x16x32_bf16 v[10:13], v[142:145], v[234:237], v[10:13]
	v_mfma_f32_16x16x32_bf16 v[14:17], v[134:137], v[234:237], v[14:17]
	s_setprio 0
	s_setprio 1
	v_mfma_f32_16x16x32_bf16 v[54:57], v[146:149], v[186:189], v[54:57]
	v_mfma_f32_16x16x32_bf16 v[50:53], v[154:157], v[186:189], v[50:53]
	v_mfma_f32_16x16x32_bf16 v[34:37], v[154:157], v[194:197], v[34:37]
	v_mfma_f32_16x16x32_bf16 v[38:41], v[146:149], v[194:197], v[38:41]
	v_mfma_f32_16x16x32_bf16 v[22:25], v[146:149], v[222:225], v[22:25]
	v_mfma_f32_16x16x32_bf16 v[18:21], v[154:157], v[222:225], v[18:21]
	v_mfma_f32_16x16x32_bf16 v[2:5], v[154:157], v[230:233], v[2:5]
	v_mfma_f32_16x16x32_bf16 v[6:9], v[146:149], v[230:233], v[6:9]
	v_mfma_f32_16x16x32_bf16 v[54:57], v[150:153], v[190:193], v[54:57]
	v_mfma_f32_16x16x32_bf16 v[50:53], v[182:185], v[190:193], v[50:53]
	v_mfma_f32_16x16x32_bf16 v[34:37], v[182:185], v[218:221], v[34:37]
	v_mfma_f32_16x16x32_bf16 v[38:41], v[150:153], v[218:221], v[38:41]
	v_mfma_f32_16x16x32_bf16 v[22:25], v[150:153], v[226:229], v[22:25]
	v_mfma_f32_16x16x32_bf16 v[18:21], v[182:185], v[226:229], v[18:21]
	v_mfma_f32_16x16x32_bf16 v[2:5], v[182:185], v[234:237], v[2:5]
	v_mfma_f32_16x16x32_bf16 v[6:9], v[150:153], v[234:237], v[6:9]
	s_setprio 0
	s_barrier
	s_add_i32 s54, 0, 0x18000
	s_add_i32 s55, 0, 0x1c000
	v_add_u32_e32 v142, s54, v199
	v_add_u32_e32 v182, s55, v199
	ds_read_b128 v[122:125], v142
	ds_read_b128 v[134:137], v142 offset:1024
	ds_read_b128 v[138:141], v142 offset:2048
	ds_read_b128 v[142:145], v142 offset:3072
	ds_read_b128 v[146:149], v182
	ds_read_b128 v[150:153], v182 offset:1024
	ds_read_b128 v[154:157], v182 offset:2048
	ds_read_b128 v[182:185], v182 offset:3072
	s_add_u32 s22, s28, 0x160000
	s_addc_u32 s23, s29, 0
	s_mov_b32 m0, s48
	v_lshl_add_u64 v[246:247], s[22:23], 0, v[162:163]
	ds_read_b128 v[186:189], v202 offset:32768
	ds_read_b128 v[190:193], v202 offset:33792
	ds_read_b128 v[194:197], v202 offset:34816
	ds_read_b128 v[218:221], v202 offset:35840
	ds_read_b128 v[222:225], v202 offset:36864
	ds_read_b128 v[226:229], v202 offset:37888
	ds_read_b128 v[230:233], v202 offset:38912
	ds_read_b128 v[234:237], v202 offset:39936
	global_load_lds_dwordx4 v[246:247], off
	v_lshl_add_u64 v[246:247], s[22:23], 0, v[160:161]
	s_mov_b32 m0, s49
	s_nop 0
	global_load_lds_dwordx4 v[246:247], off
	s_waitcnt vmcnt(8)
	s_waitcnt lgkmcnt(0)
	s_barrier
	s_setprio 1
	s_waitcnt lgkmcnt(0)
	v_mfma_f32_16x16x32_bf16 v[130:133], v[122:125], v[186:189], v[130:133]
	v_mfma_f32_16x16x32_bf16 v[126:129], v[138:141], v[186:189], v[126:129]
	v_mfma_f32_16x16x32_bf16 v[106:109], v[138:141], v[194:197], v[106:109]
	v_mfma_f32_16x16x32_bf16 v[110:113], v[122:125], v[194:197], v[110:113]
	v_mfma_f32_16x16x32_bf16 v[94:97], v[122:125], v[222:225], v[94:97]
	v_mfma_f32_16x16x32_bf16 v[90:93], v[138:141], v[222:225], v[90:93]
	v_mfma_f32_16x16x32_bf16 v[74:77], v[138:141], v[230:233], v[74:77]
	v_mfma_f32_16x16x32_bf16 v[78:81], v[122:125], v[230:233], v[78:81]
	v_mfma_f32_16x16x32_bf16 v[130:133], v[134:137], v[190:193], v[130:133]
	v_mfma_f32_16x16x32_bf16 v[126:129], v[142:145], v[190:193], v[126:129]
	v_mfma_f32_16x16x32_bf16 v[106:109], v[142:145], v[218:221], v[106:109]
	v_mfma_f32_16x16x32_bf16 v[110:113], v[134:137], v[218:221], v[110:113]
	v_mfma_f32_16x16x32_bf16 v[94:97], v[134:137], v[226:229], v[94:97]
	v_mfma_f32_16x16x32_bf16 v[90:93], v[142:145], v[226:229], v[90:93]
	v_mfma_f32_16x16x32_bf16 v[74:77], v[142:145], v[234:237], v[74:77]
	v_mfma_f32_16x16x32_bf16 v[78:81], v[134:137], v[234:237], v[78:81]
	s_setprio 0
	s_setprio 1
	v_mfma_f32_16x16x32_bf16 v[118:121], v[146:149], v[186:189], v[118:121]
	v_mfma_f32_16x16x32_bf16 v[114:117], v[154:157], v[186:189], v[114:117]
	v_mfma_f32_16x16x32_bf16 v[98:101], v[154:157], v[194:197], v[98:101]
	v_mfma_f32_16x16x32_bf16 v[102:105], v[146:149], v[194:197], v[102:105]
	v_mfma_f32_16x16x32_bf16 v[86:89], v[146:149], v[222:225], v[86:89]
	v_mfma_f32_16x16x32_bf16 v[82:85], v[154:157], v[222:225], v[82:85]
	v_mfma_f32_16x16x32_bf16 v[66:69], v[154:157], v[230:233], v[66:69]
	v_mfma_f32_16x16x32_bf16 v[70:73], v[146:149], v[230:233], v[70:73]
	v_mfma_f32_16x16x32_bf16 v[118:121], v[150:153], v[190:193], v[118:121]
	v_mfma_f32_16x16x32_bf16 v[114:117], v[182:185], v[190:193], v[114:117]
	v_mfma_f32_16x16x32_bf16 v[98:101], v[182:185], v[218:221], v[98:101]
	v_mfma_f32_16x16x32_bf16 v[102:105], v[150:153], v[218:221], v[102:105]
	v_mfma_f32_16x16x32_bf16 v[86:89], v[150:153], v[226:229], v[86:89]
	v_mfma_f32_16x16x32_bf16 v[82:85], v[182:185], v[226:229], v[82:85]
	v_mfma_f32_16x16x32_bf16 v[66:69], v[182:185], v[234:237], v[66:69]
	v_mfma_f32_16x16x32_bf16 v[70:73], v[150:153], v[234:237], v[70:73]
	s_setprio 0
	s_barrier
; #define PG8_STAGE(bufoff, gbase, voff) do { _Pragma("unroll") for (int _i = 0; _i < 2; ++_i) \
;         __builtin_amdgcn_global_load_lds((const unsigned*)((const char*)(gbase) + (voff)[_i]), (PG8_LAS unsigned*)(lds + (bufoff) + ldsw + _i * 8192), 16, 0, 0); } while (0)
; #define PG8_LDA(dst, b, h) do { _Pragma("unroll") for (int m = 0; m < 4; ++m) _Pragma("unroll") for (int k = 0; k < 2; ++k) dst[m][k] = *(const PG8_LAS bf16x8*)(lds + PG8_SA(b, h) + aoff + m * 2048 + k * 1024); } while (0)
; #define PG8_MMA(ai, bj, At, Bt) do { __builtin_amdgcn_s_setprio(1); _Pragma("unroll") for (int m = 0; m < 4; ++m) _Pragma("unroll") for (int n = 0; n < 2; ++n) _Pragma("unroll") for (int k = 0; k < 2; ++k) \
;         acc[ai][bj][m][n] = __builtin_amdgcn_mfma_f32_16x16x32_bf16(Bt[n][k], At[m][k], acc[ai][bj][m][n], 0, 0, 0); __builtin_amdgcn_s_setprio(0); } while (0)
; #define PG8_WAIT_V(n) asm volatile("s_waitcnt vmcnt(" #n ")" ::: "memory")
; #define PG8_WAIT_L(n) asm volatile("s_waitcnt lgkmcnt(" #n ")" ::: "memory")
; #define PG8_BAR __builtin_amdgcn_s_barrier()
; #define PG8_SCHED __builtin_amdgcn_sched_barrier(0)
; template <class Epi, class Sched, bool ALIGN_EPI = false, bool SP2 = false>
; __device__ __forceinline__ void gemm_phase(PG8_LAS unsigned char* lds, const Gemm g, const Sched& S, const Epi& E) {
;     ...
;             PG8_LDA(At, 1, 1); PG8_STAGE(PG8_SB(1, 0), b3, voffB); PG8_STAGE(PG8_SB(1, 1), b3 + hstep, voffB); PG8_STAGE(PG8_SA(1, 0), a3, voffA);
;             PG8_WAIT_V(8); PG8_WAIT_L(0); PG8_BAR; PG8_MMA(1, 0, At, B0); PG8_MMA(1, 1, At, B1); PG8_BAR; PG8_SCHED;
	s_add_i32 s22, s54, s2
	v_lshl_add_u64 v[238:239], v[238:239], 0, s[34:35]
	s_mov_b32 m0, s22
	ds_read_b128 v[186:189], v202 offset:49152
	ds_read_b128 v[190:193], v202 offset:50176
	ds_read_b128 v[194:197], v202 offset:51200
	ds_read_b128 v[218:221], v202 offset:52224
	ds_read_b128 v[222:225], v202 offset:53248
	ds_read_b128 v[226:229], v202 offset:54272
	ds_read_b128 v[230:233], v202 offset:55296
	ds_read_b128 v[234:237], v202 offset:56320
	global_load_lds_dwordx4 v[238:239], off
	s_add_i32 m0, s22, 0x2000
	s_add_u32 s22, s26, 0x160080
	v_lshl_add_u64 v[238:239], v[240:241], 0, s[34:35]
	s_addc_u32 s23, s27, 0
	s_add_i32 s26, s55, s2
	global_load_lds_dwordx4 v[238:239], off
	v_lshl_add_u64 v[238:239], s[22:23], 0, v[0:1]
	s_mov_b32 m0, s26
	s_nop 0
	global_load_lds_dwordx4 v[238:239], off
	v_lshl_add_u64 v[238:239], s[22:23], 0, v[158:159]
	s_add_i32 m0, s26, 0x2000
	s_nop 0
	global_load_lds_dwordx4 v[238:239], off
	v_lshl_add_u64 v[238:239], v[242:243], 0, s[34:35]
	s_mov_b32 m0, s51
	s_nop 0
	global_load_lds_dwordx4 v[238:239], off
	v_lshl_add_u64 v[238:239], v[244:245], 0, s[34:35]
	s_mov_b32 m0, s52
	s_nop 0
	global_load_lds_dwordx4 v[238:239], off
	s_waitcnt vmcnt(8)
	s_waitcnt lgkmcnt(0)
	s_barrier
	s_setprio 1
	s_waitcnt lgkmcnt(0)
	v_mfma_f32_16x16x32_bf16 v[62:65], v[122:125], v[186:189], v[62:65]
	v_mfma_f32_16x16x32_bf16 v[58:61], v[138:141], v[186:189], v[58:61]
	v_mfma_f32_16x16x32_bf16 v[42:45], v[138:141], v[194:197], v[42:45]
	v_mfma_f32_16x16x32_bf16 v[46:49], v[122:125], v[194:197], v[46:49]
	v_mfma_f32_16x16x32_bf16 v[30:33], v[122:125], v[222:225], v[30:33]
	v_mfma_f32_16x16x32_bf16 v[26:29], v[138:141], v[222:225], v[26:29]
	v_mfma_f32_16x16x32_bf16 v[10:13], v[138:141], v[230:233], v[10:13]
	v_mfma_f32_16x16x32_bf16 v[14:17], v[122:125], v[230:233], v[14:17]
	v_mfma_f32_16x16x32_bf16 v[62:65], v[134:137], v[190:193], v[62:65]
	v_mfma_f32_16x16x32_bf16 v[58:61], v[142:145], v[190:193], v[58:61]
	v_mfma_f32_16x16x32_bf16 v[42:45], v[142:145], v[218:221], v[42:45]
	v_mfma_f32_16x16x32_bf16 v[46:49], v[134:137], v[218:221], v[46:49]
	v_mfma_f32_16x16x32_bf16 v[30:33], v[134:137], v[226:229], v[30:33]
	v_mfma_f32_16x16x32_bf16 v[26:29], v[142:145], v[226:229], v[26:29]
	v_mfma_f32_16x16x32_bf16 v[10:13], v[142:145], v[234:237], v[10:13]
	v_mfma_f32_16x16x32_bf16 v[14:17], v[134:137], v[234:237], v[14:17]
	s_setprio 0
	s_setprio 1
	v_mfma_f32_16x16x32_bf16 v[54:57], v[146:149], v[186:189], v[54:57]
	v_mfma_f32_16x16x32_bf16 v[50:53], v[154:157], v[186:189], v[50:53]
	v_mfma_f32_16x16x32_bf16 v[34:37], v[154:157], v[194:197], v[34:37]
	v_mfma_f32_16x16x32_bf16 v[38:41], v[146:149], v[194:197], v[38:41]
	v_mfma_f32_16x16x32_bf16 v[22:25], v[146:149], v[222:225], v[22:25]
	v_mfma_f32_16x16x32_bf16 v[18:21], v[154:157], v[222:225], v[18:21]
	v_mfma_f32_16x16x32_bf16 v[2:5], v[154:157], v[230:233], v[2:5]
	v_mfma_f32_16x16x32_bf16 v[6:9], v[146:149], v[230:233], v[6:9]
	v_mfma_f32_16x16x32_bf16 v[54:57], v[150:153], v[190:193], v[54:57]
	v_mfma_f32_16x16x32_bf16 v[50:53], v[182:185], v[190:193], v[50:53]
	v_mfma_f32_16x16x32_bf16 v[34:37], v[182:185], v[218:221], v[34:37]
	v_mfma_f32_16x16x32_bf16 v[38:41], v[150:153], v[218:221], v[38:41]
	v_mfma_f32_16x16x32_bf16 v[22:25], v[150:153], v[226:229], v[22:25]
	v_mfma_f32_16x16x32_bf16 v[18:21], v[182:185], v[226:229], v[18:21]
	v_mfma_f32_16x16x32_bf16 v[2:5], v[182:185], v[234:237], v[2:5]
	v_mfma_f32_16x16x32_bf16 v[6:9], v[150:153], v[234:237], v[6:9]
	s_setprio 0
	s_barrier
	s_add_i32 s78, s78, 2
	s_add_u32 s44, s44, 0x100
	s_addc_u32 s45, s45, 0
	s_cmpk_gt_u32 s78, 0x55
	s_mov_b64 s[22:23], s[24:25]
	s_cbranch_scc0 .LBB0_802
	s_and_b64 vcc, exec, s[6:7]
	s_cbranch_vccz .LBB0_805
	s_barrier
